# ATTN P.V moved from packed f32 VALU FMAs to f32 matrix cores (v_mfma_f32_4x4x1_16b_f32, one key per block, bit-identical f32 fma chain); p read as one dword per lane
# baseline (speedup 1.0000x reference)
; DI void attn_item(const P& p, int b, int kvh, int quad4, char* smem, const AttnPre& pre) {
;     ...
;   const unsigned char* vb = p.v8 + ((size_t)b * SEQ) * 256 + kvh * 128 + r * 8;
; #pragma unroll 1
;   for (int n0 = 0; n0 < 256; n0 += 64) {
;     uint2 vv[16];
; #pragma unroll
;     for (int u = 0; u < 16; ++u) vv[u] = *(const uint2*)(vb + (size_t)idx[n0 + 4 * u + quad] * 256);
; #pragma unroll
;     for (int u = 0; u < 16; ++u) {
;       const float4 p4 = *(const float4*)(L + (n0 + 4 * u + quad) * 4);
;       const f32x2_t c0 = __builtin_amdgcn_cvt_pk_f32_fp8((int)vv[u].x, false), c1 = __builtin_amdgcn_cvt_pk_f32_fp8((int)vv[u].x, true);
;       const f32x2_t c2 = __builtin_amdgcn_cvt_pk_f32_fp8((int)vv[u].y, false), c3 = __builtin_amdgcn_cvt_pk_f32_fp8((int)vv[u].y, true);
;       const float vf[8] = {c0.x, c0.y, c1.x, c1.y, c2.x, c2.y, c3.x, c3.y};
; #pragma unroll
;       for (int e = 0; e < 8; ++e) {
;         o[0][e] = fmaf(p4.x, vf[e], o[0][e]); o[1][e] = fmaf(p4.y, vf[e], o[1][e]);
;         o[2][e] = fmaf(p4.z, vf[e], o[2][e]); o[3][e] = fmaf(p4.w, vf[e], o[3][e]);
;       }
;     }
.LBB0_346:
	v_readlane_b32 s6, v250, 15
	v_readlane_b32 s7, v250, 16
	s_add_u32 s6, s6, s10
	s_addc_u32 s7, s7, s11
	v_subrev_u32_e32 v168, s6, v24
	v_and_b32_e32 v169, 3, v102
	v_lshl_add_u32 v169, v169, 2, v87
	ds_read2_b32 v[152:153], v86 offset0:0 offset1:4
	ds_read2_b32 v[154:155], v86 offset0:8 offset1:12
	ds_read2_b32 v[156:157], v86 offset0:16 offset1:20
	ds_read2_b32 v[158:159], v86 offset0:24 offset1:28
	ds_read2_b32 v[160:161], v86 offset0:32 offset1:36
	ds_read2_b32 v[162:163], v86 offset0:40 offset1:44
	ds_read2_b32 v[164:165], v86 offset0:48 offset1:52
	ds_read2_b32 v[166:167], v86 offset0:56 offset1:60
	s_waitcnt lgkmcnt(0)
	v_lshl_add_u32 v152, v152, 8, v168
	v_lshl_add_u32 v153, v153, 8, v168
	v_lshl_add_u32 v154, v154, 8, v168
	v_lshl_add_u32 v155, v155, 8, v168
	v_lshl_add_u32 v156, v156, 8, v168
	v_lshl_add_u32 v157, v157, 8, v168
	v_lshl_add_u32 v158, v158, 8, v168
	v_lshl_add_u32 v159, v159, 8, v168
	v_lshl_add_u32 v160, v160, 8, v168
	v_lshl_add_u32 v161, v161, 8, v168
	v_lshl_add_u32 v162, v162, 8, v168
	v_lshl_add_u32 v163, v163, 8, v168
	v_lshl_add_u32 v164, v164, 8, v168
	v_lshl_add_u32 v165, v165, 8, v168
	v_lshl_add_u32 v166, v166, 8, v168
	v_lshl_add_u32 v167, v167, 8, v168
	global_load_dwordx2 v[50:51], v152, s[6:7]
	global_load_dwordx2 v[52:53], v153, s[6:7]
	global_load_dwordx2 v[54:55], v154, s[6:7]
	global_load_dwordx2 v[56:57], v155, s[6:7]
	global_load_dwordx2 v[58:59], v156, s[6:7]
	global_load_dwordx2 v[60:61], v157, s[6:7]
	global_load_dwordx2 v[62:63], v158, s[6:7]
	global_load_dwordx2 v[64:65], v159, s[6:7]
	global_load_dwordx2 v[66:67], v160, s[6:7]
	global_load_dwordx2 v[68:69], v161, s[6:7]
	global_load_dwordx2 v[70:71], v162, s[6:7]
	global_load_dwordx2 v[72:73], v163, s[6:7]
	global_load_dwordx2 v[74:75], v164, s[6:7]
	global_load_dwordx2 v[76:77], v165, s[6:7]
	global_load_dwordx2 v[78:79], v166, s[6:7]
	global_load_dwordx2 v[80:81], v167, s[6:7]
	ds_read_b32 v92, v169
	ds_read2_b32 v[152:153], v86 offset0:64 offset1:68
	ds_read2_b32 v[154:155], v86 offset0:72 offset1:76
	ds_read2_b32 v[156:157], v86 offset0:80 offset1:84
	ds_read2_b32 v[158:159], v86 offset0:88 offset1:92
	ds_read2_b32 v[160:161], v86 offset0:96 offset1:100
	ds_read2_b32 v[162:163], v86 offset0:104 offset1:108
	ds_read2_b32 v[164:165], v86 offset0:112 offset1:116
	ds_read2_b32 v[166:167], v86 offset0:120 offset1:124
	s_waitcnt lgkmcnt(0)
	v_lshl_add_u32 v152, v152, 8, v168
	v_lshl_add_u32 v153, v153, 8, v168
	v_lshl_add_u32 v154, v154, 8, v168
	v_lshl_add_u32 v155, v155, 8, v168
	v_lshl_add_u32 v156, v156, 8, v168
	v_lshl_add_u32 v157, v157, 8, v168
	v_lshl_add_u32 v158, v158, 8, v168
	v_lshl_add_u32 v159, v159, 8, v168
	v_lshl_add_u32 v160, v160, 8, v168
	v_lshl_add_u32 v161, v161, 8, v168
	v_lshl_add_u32 v162, v162, 8, v168
	v_lshl_add_u32 v163, v163, 8, v168
	v_lshl_add_u32 v164, v164, 8, v168
	v_lshl_add_u32 v165, v165, 8, v168
	v_lshl_add_u32 v166, v166, 8, v168
	v_lshl_add_u32 v167, v167, 8, v168
	global_load_dwordx2 v[120:121], v152, s[6:7]
	global_load_dwordx2 v[122:123], v153, s[6:7]
	global_load_dwordx2 v[124:125], v154, s[6:7]
	global_load_dwordx2 v[126:127], v155, s[6:7]
	global_load_dwordx2 v[128:129], v156, s[6:7]
	global_load_dwordx2 v[130:131], v157, s[6:7]
	global_load_dwordx2 v[132:133], v158, s[6:7]
	global_load_dwordx2 v[134:135], v159, s[6:7]
	global_load_dwordx2 v[136:137], v160, s[6:7]
	global_load_dwordx2 v[138:139], v161, s[6:7]
	global_load_dwordx2 v[140:141], v162, s[6:7]
	global_load_dwordx2 v[142:143], v163, s[6:7]
	global_load_dwordx2 v[144:145], v164, s[6:7]
	global_load_dwordx2 v[146:147], v165, s[6:7]
	global_load_dwordx2 v[148:149], v166, s[6:7]
	global_load_dwordx2 v[150:151], v167, s[6:7]
	ds_read_b32 v93, v169 offset:64
	s_waitcnt vmcnt(31) lgkmcnt(1)
	v_cvt_pk_f32_fp8_e32 v[100:101], v50
	v_cvt_pk_f32_fp8_sdwa v[102:103], v50 src0_sel:WORD_1
	v_cvt_pk_f32_fp8_e32 v[104:105], v51
	v_cvt_pk_f32_fp8_sdwa v[106:107], v51 src0_sel:WORD_1
	v_mfma_f32_4x4x1_16b_f32 v[194:197], v92, v100, 0
	v_mfma_f32_4x4x1_16b_f32 v[198:201], v92, v101, 0
	v_mfma_f32_4x4x1_16b_f32 v[202:205], v92, v102, 0
	v_mfma_f32_4x4x1_16b_f32 v[206:209], v92, v103, 0
	v_mfma_f32_4x4x1_16b_f32 v[210:213], v92, v104, 0
	v_mfma_f32_4x4x1_16b_f32 v[214:217], v92, v105, 0
	v_mfma_f32_4x4x1_16b_f32 v[228:231], v92, v106, 0
	v_mfma_f32_4x4x1_16b_f32 v[232:235], v92, v107, 0
	ds_read_b32 v92, v169 offset:128
	s_waitcnt vmcnt(30) lgkmcnt(1)
	v_cvt_pk_f32_fp8_e32 v[100:101], v52
	v_cvt_pk_f32_fp8_sdwa v[102:103], v52 src0_sel:WORD_1
	v_cvt_pk_f32_fp8_e32 v[104:105], v53
	v_cvt_pk_f32_fp8_sdwa v[106:107], v53 src0_sel:WORD_1
	v_mfma_f32_4x4x1_16b_f32 v[194:197], v93, v100, v[194:197]
	v_mfma_f32_4x4x1_16b_f32 v[198:201], v93, v101, v[198:201]
	v_mfma_f32_4x4x1_16b_f32 v[202:205], v93, v102, v[202:205]
	v_mfma_f32_4x4x1_16b_f32 v[206:209], v93, v103, v[206:209]
	v_mfma_f32_4x4x1_16b_f32 v[210:213], v93, v104, v[210:213]
	v_mfma_f32_4x4x1_16b_f32 v[214:217], v93, v105, v[214:217]
	v_mfma_f32_4x4x1_16b_f32 v[228:231], v93, v106, v[228:231]
	v_mfma_f32_4x4x1_16b_f32 v[232:235], v93, v107, v[232:235]
	ds_read_b32 v93, v169 offset:192
	s_waitcnt vmcnt(29) lgkmcnt(1)
	v_cvt_pk_f32_fp8_e32 v[100:101], v54
	v_cvt_pk_f32_fp8_sdwa v[102:103], v54 src0_sel:WORD_1
	v_cvt_pk_f32_fp8_e32 v[104:105], v55
	v_cvt_pk_f32_fp8_sdwa v[106:107], v55 src0_sel:WORD_1
	v_mfma_f32_4x4x1_16b_f32 v[194:197], v92, v100, v[194:197]
	v_mfma_f32_4x4x1_16b_f32 v[198:201], v92, v101, v[198:201]
	v_mfma_f32_4x4x1_16b_f32 v[202:205], v92, v102, v[202:205]
	v_mfma_f32_4x4x1_16b_f32 v[206:209], v92, v103, v[206:209]
	v_mfma_f32_4x4x1_16b_f32 v[210:213], v92, v104, v[210:213]
	v_mfma_f32_4x4x1_16b_f32 v[214:217], v92, v105, v[214:217]
	v_mfma_f32_4x4x1_16b_f32 v[228:231], v92, v106, v[228:231]
	v_mfma_f32_4x4x1_16b_f32 v[232:235], v92, v107, v[232:235]
	ds_read_b32 v92, v169 offset:256
	s_waitcnt vmcnt(28) lgkmcnt(1)
; DI void attn_item(const P& p, int b, int kvh, int quad4, char* smem, const AttnPre& pre) {
;     ...
;   for (int n0 = 0; n0 < 256; n0 += 64) {
;     uint2 vv[16];
; #pragma unroll
;     for (int u = 0; u < 16; ++u) vv[u] = *(const uint2*)(vb + (size_t)idx[n0 + 4 * u + quad] * 256);
; #pragma unroll
;     for (int u = 0; u < 16; ++u) {
;       const float4 p4 = *(const float4*)(L + (n0 + 4 * u + quad) * 4);
;       const f32x2_t c0 = __builtin_amdgcn_cvt_pk_f32_fp8((int)vv[u].x, false), c1 = __builtin_amdgcn_cvt_pk_f32_fp8((int)vv[u].x, true);
;       const f32x2_t c2 = __builtin_amdgcn_cvt_pk_f32_fp8((int)vv[u].y, false), c3 = __builtin_amdgcn_cvt_pk_f32_fp8((int)vv[u].y, true);
;       const float vf[8] = {c0.x, c0.y, c1.x, c1.y, c2.x, c2.y, c3.x, c3.y};
; #pragma unroll
;       for (int e = 0; e < 8; ++e) {
;         o[0][e] = fmaf(p4.x, vf[e], o[0][e]); o[1][e] = fmaf(p4.y, vf[e], o[1][e]);
;         o[2][e] = fmaf(p4.z, vf[e], o[2][e]); o[3][e] = fmaf(p4.w, vf[e], o[3][e]);
;       }
;     }
	v_cvt_pk_f32_fp8_e32 v[100:101], v56
	v_cvt_pk_f32_fp8_sdwa v[102:103], v56 src0_sel:WORD_1
	v_cvt_pk_f32_fp8_e32 v[104:105], v57
	v_cvt_pk_f32_fp8_sdwa v[106:107], v57 src0_sel:WORD_1
	v_mfma_f32_4x4x1_16b_f32 v[194:197], v93, v100, v[194:197]
	v_mfma_f32_4x4x1_16b_f32 v[198:201], v93, v101, v[198:201]
	v_mfma_f32_4x4x1_16b_f32 v[202:205], v93, v102, v[202:205]
	v_mfma_f32_4x4x1_16b_f32 v[206:209], v93, v103, v[206:209]
	v_mfma_f32_4x4x1_16b_f32 v[210:213], v93, v104, v[210:213]
	v_mfma_f32_4x4x1_16b_f32 v[214:217], v93, v105, v[214:217]
	v_mfma_f32_4x4x1_16b_f32 v[228:231], v93, v106, v[228:231]
	v_mfma_f32_4x4x1_16b_f32 v[232:235], v93, v107, v[232:235]
	ds_read_b32 v93, v169 offset:320
	s_waitcnt vmcnt(27) lgkmcnt(1)
	v_cvt_pk_f32_fp8_e32 v[100:101], v58
	v_cvt_pk_f32_fp8_sdwa v[102:103], v58 src0_sel:WORD_1
	v_cvt_pk_f32_fp8_e32 v[104:105], v59
	v_cvt_pk_f32_fp8_sdwa v[106:107], v59 src0_sel:WORD_1
	v_mfma_f32_4x4x1_16b_f32 v[194:197], v92, v100, v[194:197]
	v_mfma_f32_4x4x1_16b_f32 v[198:201], v92, v101, v[198:201]
	v_mfma_f32_4x4x1_16b_f32 v[202:205], v92, v102, v[202:205]
	v_mfma_f32_4x4x1_16b_f32 v[206:209], v92, v103, v[206:209]
	v_mfma_f32_4x4x1_16b_f32 v[210:213], v92, v104, v[210:213]
	v_mfma_f32_4x4x1_16b_f32 v[214:217], v92, v105, v[214:217]
	v_mfma_f32_4x4x1_16b_f32 v[228:231], v92, v106, v[228:231]
	v_mfma_f32_4x4x1_16b_f32 v[232:235], v92, v107, v[232:235]
	ds_read_b32 v92, v169 offset:384
	s_waitcnt vmcnt(26) lgkmcnt(1)
	v_cvt_pk_f32_fp8_e32 v[100:101], v60
	v_cvt_pk_f32_fp8_sdwa v[102:103], v60 src0_sel:WORD_1
	v_cvt_pk_f32_fp8_e32 v[104:105], v61
	v_cvt_pk_f32_fp8_sdwa v[106:107], v61 src0_sel:WORD_1
	v_mfma_f32_4x4x1_16b_f32 v[194:197], v93, v100, v[194:197]
	v_mfma_f32_4x4x1_16b_f32 v[198:201], v93, v101, v[198:201]
	v_mfma_f32_4x4x1_16b_f32 v[202:205], v93, v102, v[202:205]
	v_mfma_f32_4x4x1_16b_f32 v[206:209], v93, v103, v[206:209]
	v_mfma_f32_4x4x1_16b_f32 v[210:213], v93, v104, v[210:213]
	v_mfma_f32_4x4x1_16b_f32 v[214:217], v93, v105, v[214:217]
	v_mfma_f32_4x4x1_16b_f32 v[228:231], v93, v106, v[228:231]
	v_mfma_f32_4x4x1_16b_f32 v[232:235], v93, v107, v[232:235]
	ds_read_b32 v93, v169 offset:448
	s_waitcnt vmcnt(25) lgkmcnt(1)
	v_cvt_pk_f32_fp8_e32 v[100:101], v62
	v_cvt_pk_f32_fp8_sdwa v[102:103], v62 src0_sel:WORD_1
	v_cvt_pk_f32_fp8_e32 v[104:105], v63
	v_cvt_pk_f32_fp8_sdwa v[106:107], v63 src0_sel:WORD_1
	v_mfma_f32_4x4x1_16b_f32 v[194:197], v92, v100, v[194:197]
	v_mfma_f32_4x4x1_16b_f32 v[198:201], v92, v101, v[198:201]
	v_mfma_f32_4x4x1_16b_f32 v[202:205], v92, v102, v[202:205]
	v_mfma_f32_4x4x1_16b_f32 v[206:209], v92, v103, v[206:209]
	v_mfma_f32_4x4x1_16b_f32 v[210:213], v92, v104, v[210:213]
	v_mfma_f32_4x4x1_16b_f32 v[214:217], v92, v105, v[214:217]
	v_mfma_f32_4x4x1_16b_f32 v[228:231], v92, v106, v[228:231]
	v_mfma_f32_4x4x1_16b_f32 v[232:235], v92, v107, v[232:235]
	ds_read_b32 v92, v169 offset:512
	s_waitcnt vmcnt(24) lgkmcnt(1)
	v_cvt_pk_f32_fp8_e32 v[100:101], v64
	v_cvt_pk_f32_fp8_sdwa v[102:103], v64 src0_sel:WORD_1
	v_cvt_pk_f32_fp8_e32 v[104:105], v65
	v_cvt_pk_f32_fp8_sdwa v[106:107], v65 src0_sel:WORD_1
	v_mfma_f32_4x4x1_16b_f32 v[194:197], v93, v100, v[194:197]
	v_mfma_f32_4x4x1_16b_f32 v[198:201], v93, v101, v[198:201]
	v_mfma_f32_4x4x1_16b_f32 v[202:205], v93, v102, v[202:205]
	v_mfma_f32_4x4x1_16b_f32 v[206:209], v93, v103, v[206:209]
	v_mfma_f32_4x4x1_16b_f32 v[210:213], v93, v104, v[210:213]
	v_mfma_f32_4x4x1_16b_f32 v[214:217], v93, v105, v[214:217]
	v_mfma_f32_4x4x1_16b_f32 v[228:231], v93, v106, v[228:231]
	v_mfma_f32_4x4x1_16b_f32 v[232:235], v93, v107, v[232:235]
	ds_read_b32 v93, v169 offset:576
	s_waitcnt vmcnt(23) lgkmcnt(1)
	v_cvt_pk_f32_fp8_e32 v[100:101], v66
	v_cvt_pk_f32_fp8_sdwa v[102:103], v66 src0_sel:WORD_1
	v_cvt_pk_f32_fp8_e32 v[104:105], v67
	v_cvt_pk_f32_fp8_sdwa v[106:107], v67 src0_sel:WORD_1
	v_mfma_f32_4x4x1_16b_f32 v[194:197], v92, v100, v[194:197]
	v_mfma_f32_4x4x1_16b_f32 v[198:201], v92, v101, v[198:201]
	v_mfma_f32_4x4x1_16b_f32 v[202:205], v92, v102, v[202:205]
	v_mfma_f32_4x4x1_16b_f32 v[206:209], v92, v103, v[206:209]
	v_mfma_f32_4x4x1_16b_f32 v[210:213], v92, v104, v[210:213]
	v_mfma_f32_4x4x1_16b_f32 v[214:217], v92, v105, v[214:217]
	v_mfma_f32_4x4x1_16b_f32 v[228:231], v92, v106, v[228:231]
	v_mfma_f32_4x4x1_16b_f32 v[232:235], v92, v107, v[232:235]
	ds_read_b32 v92, v169 offset:640
	s_waitcnt vmcnt(22) lgkmcnt(1)
	v_cvt_pk_f32_fp8_e32 v[100:101], v68
	v_cvt_pk_f32_fp8_sdwa v[102:103], v68 src0_sel:WORD_1
	v_cvt_pk_f32_fp8_e32 v[104:105], v69
	v_cvt_pk_f32_fp8_sdwa v[106:107], v69 src0_sel:WORD_1
	v_mfma_f32_4x4x1_16b_f32 v[194:197], v93, v100, v[194:197]
	v_mfma_f32_4x4x1_16b_f32 v[198:201], v93, v101, v[198:201]
	v_mfma_f32_4x4x1_16b_f32 v[202:205], v93, v102, v[202:205]
	v_mfma_f32_4x4x1_16b_f32 v[206:209], v93, v103, v[206:209]
	v_mfma_f32_4x4x1_16b_f32 v[210:213], v93, v104, v[210:213]
	v_mfma_f32_4x4x1_16b_f32 v[214:217], v93, v105, v[214:217]
	v_mfma_f32_4x4x1_16b_f32 v[228:231], v93, v106, v[228:231]
	v_mfma_f32_4x4x1_16b_f32 v[232:235], v93, v107, v[232:235]
	ds_read_b32 v93, v169 offset:704
	s_waitcnt vmcnt(21) lgkmcnt(1)
	v_cvt_pk_f32_fp8_e32 v[100:101], v70
	v_cvt_pk_f32_fp8_sdwa v[102:103], v70 src0_sel:WORD_1
	v_cvt_pk_f32_fp8_e32 v[104:105], v71
	v_cvt_pk_f32_fp8_sdwa v[106:107], v71 src0_sel:WORD_1
	v_mfma_f32_4x4x1_16b_f32 v[194:197], v92, v100, v[194:197]
	v_mfma_f32_4x4x1_16b_f32 v[198:201], v92, v101, v[198:201]
	v_mfma_f32_4x4x1_16b_f32 v[202:205], v92, v102, v[202:205]
	v_mfma_f32_4x4x1_16b_f32 v[206:209], v92, v103, v[206:209]
	v_mfma_f32_4x4x1_16b_f32 v[210:213], v92, v104, v[210:213]
	v_mfma_f32_4x4x1_16b_f32 v[214:217], v92, v105, v[214:217]
	v_mfma_f32_4x4x1_16b_f32 v[228:231], v92, v106, v[228:231]
	v_mfma_f32_4x4x1_16b_f32 v[232:235], v92, v107, v[232:235]
	ds_read_b32 v92, v169 offset:768
	s_waitcnt vmcnt(20) lgkmcnt(1)
; DI void attn_item(const P& p, int b, int kvh, int quad4, char* smem, const AttnPre& pre) {
;     ...
;   for (int n0 = 0; n0 < 256; n0 += 64) {
;     uint2 vv[16];
; #pragma unroll
;     for (int u = 0; u < 16; ++u) vv[u] = *(const uint2*)(vb + (size_t)idx[n0 + 4 * u + quad] * 256);
; #pragma unroll
;     for (int u = 0; u < 16; ++u) {
;       const float4 p4 = *(const float4*)(L + (n0 + 4 * u + quad) * 4);
;       const f32x2_t c0 = __builtin_amdgcn_cvt_pk_f32_fp8((int)vv[u].x, false), c1 = __builtin_amdgcn_cvt_pk_f32_fp8((int)vv[u].x, true);
;       const f32x2_t c2 = __builtin_amdgcn_cvt_pk_f32_fp8((int)vv[u].y, false), c3 = __builtin_amdgcn_cvt_pk_f32_fp8((int)vv[u].y, true);
;       const float vf[8] = {c0.x, c0.y, c1.x, c1.y, c2.x, c2.y, c3.x, c3.y};
; #pragma unroll
;       for (int e = 0; e < 8; ++e) {
;         o[0][e] = fmaf(p4.x, vf[e], o[0][e]); o[1][e] = fmaf(p4.y, vf[e], o[1][e]);
;         o[2][e] = fmaf(p4.z, vf[e], o[2][e]); o[3][e] = fmaf(p4.w, vf[e], o[3][e]);
;       }
;     }
	v_cvt_pk_f32_fp8_e32 v[100:101], v72
	v_cvt_pk_f32_fp8_sdwa v[102:103], v72 src0_sel:WORD_1
	v_cvt_pk_f32_fp8_e32 v[104:105], v73
	v_cvt_pk_f32_fp8_sdwa v[106:107], v73 src0_sel:WORD_1
	v_mfma_f32_4x4x1_16b_f32 v[194:197], v93, v100, v[194:197]
	v_mfma_f32_4x4x1_16b_f32 v[198:201], v93, v101, v[198:201]
	v_mfma_f32_4x4x1_16b_f32 v[202:205], v93, v102, v[202:205]
	v_mfma_f32_4x4x1_16b_f32 v[206:209], v93, v103, v[206:209]
	v_mfma_f32_4x4x1_16b_f32 v[210:213], v93, v104, v[210:213]
	v_mfma_f32_4x4x1_16b_f32 v[214:217], v93, v105, v[214:217]
	v_mfma_f32_4x4x1_16b_f32 v[228:231], v93, v106, v[228:231]
	v_mfma_f32_4x4x1_16b_f32 v[232:235], v93, v107, v[232:235]
	ds_read_b32 v93, v169 offset:832
	s_waitcnt vmcnt(19) lgkmcnt(1)
	v_cvt_pk_f32_fp8_e32 v[100:101], v74
	v_cvt_pk_f32_fp8_sdwa v[102:103], v74 src0_sel:WORD_1
	v_cvt_pk_f32_fp8_e32 v[104:105], v75
	v_cvt_pk_f32_fp8_sdwa v[106:107], v75 src0_sel:WORD_1
	v_mfma_f32_4x4x1_16b_f32 v[194:197], v92, v100, v[194:197]
	v_mfma_f32_4x4x1_16b_f32 v[198:201], v92, v101, v[198:201]
	v_mfma_f32_4x4x1_16b_f32 v[202:205], v92, v102, v[202:205]
	v_mfma_f32_4x4x1_16b_f32 v[206:209], v92, v103, v[206:209]
	v_mfma_f32_4x4x1_16b_f32 v[210:213], v92, v104, v[210:213]
	v_mfma_f32_4x4x1_16b_f32 v[214:217], v92, v105, v[214:217]
	v_mfma_f32_4x4x1_16b_f32 v[228:231], v92, v106, v[228:231]
	v_mfma_f32_4x4x1_16b_f32 v[232:235], v92, v107, v[232:235]
	ds_read_b32 v92, v169 offset:896
	s_waitcnt vmcnt(18) lgkmcnt(1)
	v_cvt_pk_f32_fp8_e32 v[100:101], v76
	v_cvt_pk_f32_fp8_sdwa v[102:103], v76 src0_sel:WORD_1
	v_cvt_pk_f32_fp8_e32 v[104:105], v77
	v_cvt_pk_f32_fp8_sdwa v[106:107], v77 src0_sel:WORD_1
	v_mfma_f32_4x4x1_16b_f32 v[194:197], v93, v100, v[194:197]
	v_mfma_f32_4x4x1_16b_f32 v[198:201], v93, v101, v[198:201]
	v_mfma_f32_4x4x1_16b_f32 v[202:205], v93, v102, v[202:205]
	v_mfma_f32_4x4x1_16b_f32 v[206:209], v93, v103, v[206:209]
	v_mfma_f32_4x4x1_16b_f32 v[210:213], v93, v104, v[210:213]
	v_mfma_f32_4x4x1_16b_f32 v[214:217], v93, v105, v[214:217]
	v_mfma_f32_4x4x1_16b_f32 v[228:231], v93, v106, v[228:231]
	v_mfma_f32_4x4x1_16b_f32 v[232:235], v93, v107, v[232:235]
	ds_read_b32 v93, v169 offset:960
	s_waitcnt vmcnt(17) lgkmcnt(1)
	v_cvt_pk_f32_fp8_e32 v[100:101], v78
	v_cvt_pk_f32_fp8_sdwa v[102:103], v78 src0_sel:WORD_1
	v_cvt_pk_f32_fp8_e32 v[104:105], v79
	v_cvt_pk_f32_fp8_sdwa v[106:107], v79 src0_sel:WORD_1
	v_mfma_f32_4x4x1_16b_f32 v[194:197], v92, v100, v[194:197]
	v_mfma_f32_4x4x1_16b_f32 v[198:201], v92, v101, v[198:201]
	v_mfma_f32_4x4x1_16b_f32 v[202:205], v92, v102, v[202:205]
	v_mfma_f32_4x4x1_16b_f32 v[206:209], v92, v103, v[206:209]
	v_mfma_f32_4x4x1_16b_f32 v[210:213], v92, v104, v[210:213]
	v_mfma_f32_4x4x1_16b_f32 v[214:217], v92, v105, v[214:217]
	v_mfma_f32_4x4x1_16b_f32 v[228:231], v92, v106, v[228:231]
	v_mfma_f32_4x4x1_16b_f32 v[232:235], v92, v107, v[232:235]
	ds_read_b32 v92, v169 offset:1024
	s_waitcnt vmcnt(16) lgkmcnt(1)
	v_cvt_pk_f32_fp8_e32 v[100:101], v80
	v_cvt_pk_f32_fp8_sdwa v[102:103], v80 src0_sel:WORD_1
	v_cvt_pk_f32_fp8_e32 v[104:105], v81
	v_cvt_pk_f32_fp8_sdwa v[106:107], v81 src0_sel:WORD_1
	v_mfma_f32_4x4x1_16b_f32 v[194:197], v93, v100, v[194:197]
	v_mfma_f32_4x4x1_16b_f32 v[198:201], v93, v101, v[198:201]
	v_mfma_f32_4x4x1_16b_f32 v[202:205], v93, v102, v[202:205]
	v_mfma_f32_4x4x1_16b_f32 v[206:209], v93, v103, v[206:209]
	v_mfma_f32_4x4x1_16b_f32 v[210:213], v93, v104, v[210:213]
	v_mfma_f32_4x4x1_16b_f32 v[214:217], v93, v105, v[214:217]
	v_mfma_f32_4x4x1_16b_f32 v[228:231], v93, v106, v[228:231]
	v_mfma_f32_4x4x1_16b_f32 v[232:235], v93, v107, v[232:235]
	ds_read2_b32 v[152:153], v86 offset0:128 offset1:132
	ds_read2_b32 v[154:155], v86 offset0:136 offset1:140
	ds_read2_b32 v[156:157], v86 offset0:144 offset1:148
	ds_read2_b32 v[158:159], v86 offset0:152 offset1:156
	ds_read2_b32 v[160:161], v86 offset0:160 offset1:164
	ds_read2_b32 v[162:163], v86 offset0:168 offset1:172
	ds_read2_b32 v[164:165], v86 offset0:176 offset1:180
	ds_read2_b32 v[166:167], v86 offset0:184 offset1:188
	s_waitcnt lgkmcnt(0)
	v_lshl_add_u32 v152, v152, 8, v168
	v_lshl_add_u32 v153, v153, 8, v168
	v_lshl_add_u32 v154, v154, 8, v168
	v_lshl_add_u32 v155, v155, 8, v168
	v_lshl_add_u32 v156, v156, 8, v168
	v_lshl_add_u32 v157, v157, 8, v168
	v_lshl_add_u32 v158, v158, 8, v168
	v_lshl_add_u32 v159, v159, 8, v168
	v_lshl_add_u32 v160, v160, 8, v168
	v_lshl_add_u32 v161, v161, 8, v168
	v_lshl_add_u32 v162, v162, 8, v168
	v_lshl_add_u32 v163, v163, 8, v168
	v_lshl_add_u32 v164, v164, 8, v168
	v_lshl_add_u32 v165, v165, 8, v168
	v_lshl_add_u32 v166, v166, 8, v168
	v_lshl_add_u32 v167, v167, 8, v168
	global_load_dwordx2 v[50:51], v152, s[6:7]
	global_load_dwordx2 v[52:53], v153, s[6:7]
	global_load_dwordx2 v[54:55], v154, s[6:7]
	global_load_dwordx2 v[56:57], v155, s[6:7]
	global_load_dwordx2 v[58:59], v156, s[6:7]
	global_load_dwordx2 v[60:61], v157, s[6:7]
	global_load_dwordx2 v[62:63], v158, s[6:7]
	global_load_dwordx2 v[64:65], v159, s[6:7]
	global_load_dwordx2 v[66:67], v160, s[6:7]
	global_load_dwordx2 v[68:69], v161, s[6:7]
	global_load_dwordx2 v[70:71], v162, s[6:7]
	global_load_dwordx2 v[72:73], v163, s[6:7]
	global_load_dwordx2 v[74:75], v164, s[6:7]
	global_load_dwordx2 v[76:77], v165, s[6:7]
	global_load_dwordx2 v[78:79], v166, s[6:7]
	global_load_dwordx2 v[80:81], v167, s[6:7]
	ds_read_b32 v93, v169 offset:1088
	s_waitcnt vmcnt(31) lgkmcnt(1)
; DI void attn_item(const P& p, int b, int kvh, int quad4, char* smem, const AttnPre& pre) {
;     ...
;   for (int n0 = 0; n0 < 256; n0 += 64) {
;     uint2 vv[16];
; #pragma unroll
;     for (int u = 0; u < 16; ++u) vv[u] = *(const uint2*)(vb + (size_t)idx[n0 + 4 * u + quad] * 256);
; #pragma unroll
;     for (int u = 0; u < 16; ++u) {
;       const float4 p4 = *(const float4*)(L + (n0 + 4 * u + quad) * 4);
;       const f32x2_t c0 = __builtin_amdgcn_cvt_pk_f32_fp8((int)vv[u].x, false), c1 = __builtin_amdgcn_cvt_pk_f32_fp8((int)vv[u].x, true);
;       const f32x2_t c2 = __builtin_amdgcn_cvt_pk_f32_fp8((int)vv[u].y, false), c3 = __builtin_amdgcn_cvt_pk_f32_fp8((int)vv[u].y, true);
;       const float vf[8] = {c0.x, c0.y, c1.x, c1.y, c2.x, c2.y, c3.x, c3.y};
; #pragma unroll
;       for (int e = 0; e < 8; ++e) {
;         o[0][e] = fmaf(p4.x, vf[e], o[0][e]); o[1][e] = fmaf(p4.y, vf[e], o[1][e]);
;         o[2][e] = fmaf(p4.z, vf[e], o[2][e]); o[3][e] = fmaf(p4.w, vf[e], o[3][e]);
;       }
;     }
	v_cvt_pk_f32_fp8_e32 v[100:101], v120
	v_cvt_pk_f32_fp8_sdwa v[102:103], v120 src0_sel:WORD_1
	v_cvt_pk_f32_fp8_e32 v[104:105], v121
	v_cvt_pk_f32_fp8_sdwa v[106:107], v121 src0_sel:WORD_1
	v_mfma_f32_4x4x1_16b_f32 v[194:197], v92, v100, v[194:197]
	v_mfma_f32_4x4x1_16b_f32 v[198:201], v92, v101, v[198:201]
	v_mfma_f32_4x4x1_16b_f32 v[202:205], v92, v102, v[202:205]
	v_mfma_f32_4x4x1_16b_f32 v[206:209], v92, v103, v[206:209]
	v_mfma_f32_4x4x1_16b_f32 v[210:213], v92, v104, v[210:213]
	v_mfma_f32_4x4x1_16b_f32 v[214:217], v92, v105, v[214:217]
	v_mfma_f32_4x4x1_16b_f32 v[228:231], v92, v106, v[228:231]
	v_mfma_f32_4x4x1_16b_f32 v[232:235], v92, v107, v[232:235]
	ds_read_b32 v92, v169 offset:1152
	s_waitcnt vmcnt(30) lgkmcnt(1)
	v_cvt_pk_f32_fp8_e32 v[100:101], v122
	v_cvt_pk_f32_fp8_sdwa v[102:103], v122 src0_sel:WORD_1
	v_cvt_pk_f32_fp8_e32 v[104:105], v123
	v_cvt_pk_f32_fp8_sdwa v[106:107], v123 src0_sel:WORD_1
	v_mfma_f32_4x4x1_16b_f32 v[194:197], v93, v100, v[194:197]
	v_mfma_f32_4x4x1_16b_f32 v[198:201], v93, v101, v[198:201]
	v_mfma_f32_4x4x1_16b_f32 v[202:205], v93, v102, v[202:205]
	v_mfma_f32_4x4x1_16b_f32 v[206:209], v93, v103, v[206:209]
	v_mfma_f32_4x4x1_16b_f32 v[210:213], v93, v104, v[210:213]
	v_mfma_f32_4x4x1_16b_f32 v[214:217], v93, v105, v[214:217]
	v_mfma_f32_4x4x1_16b_f32 v[228:231], v93, v106, v[228:231]
	v_mfma_f32_4x4x1_16b_f32 v[232:235], v93, v107, v[232:235]
	ds_read_b32 v93, v169 offset:1216
	s_waitcnt vmcnt(29) lgkmcnt(1)
	v_cvt_pk_f32_fp8_e32 v[100:101], v124
	v_cvt_pk_f32_fp8_sdwa v[102:103], v124 src0_sel:WORD_1
	v_cvt_pk_f32_fp8_e32 v[104:105], v125
	v_cvt_pk_f32_fp8_sdwa v[106:107], v125 src0_sel:WORD_1
	v_mfma_f32_4x4x1_16b_f32 v[194:197], v92, v100, v[194:197]
	v_mfma_f32_4x4x1_16b_f32 v[198:201], v92, v101, v[198:201]
	v_mfma_f32_4x4x1_16b_f32 v[202:205], v92, v102, v[202:205]
	v_mfma_f32_4x4x1_16b_f32 v[206:209], v92, v103, v[206:209]
	v_mfma_f32_4x4x1_16b_f32 v[210:213], v92, v104, v[210:213]
	v_mfma_f32_4x4x1_16b_f32 v[214:217], v92, v105, v[214:217]
	v_mfma_f32_4x4x1_16b_f32 v[228:231], v92, v106, v[228:231]
	v_mfma_f32_4x4x1_16b_f32 v[232:235], v92, v107, v[232:235]
	ds_read_b32 v92, v169 offset:1280
	s_waitcnt vmcnt(28) lgkmcnt(1)
	v_cvt_pk_f32_fp8_e32 v[100:101], v126
	v_cvt_pk_f32_fp8_sdwa v[102:103], v126 src0_sel:WORD_1
	v_cvt_pk_f32_fp8_e32 v[104:105], v127
	v_cvt_pk_f32_fp8_sdwa v[106:107], v127 src0_sel:WORD_1
	v_mfma_f32_4x4x1_16b_f32 v[194:197], v93, v100, v[194:197]
	v_mfma_f32_4x4x1_16b_f32 v[198:201], v93, v101, v[198:201]
	v_mfma_f32_4x4x1_16b_f32 v[202:205], v93, v102, v[202:205]
	v_mfma_f32_4x4x1_16b_f32 v[206:209], v93, v103, v[206:209]
	v_mfma_f32_4x4x1_16b_f32 v[210:213], v93, v104, v[210:213]
	v_mfma_f32_4x4x1_16b_f32 v[214:217], v93, v105, v[214:217]
	v_mfma_f32_4x4x1_16b_f32 v[228:231], v93, v106, v[228:231]
	v_mfma_f32_4x4x1_16b_f32 v[232:235], v93, v107, v[232:235]
	ds_read_b32 v93, v169 offset:1344
	s_waitcnt vmcnt(27) lgkmcnt(1)
	v_cvt_pk_f32_fp8_e32 v[100:101], v128
	v_cvt_pk_f32_fp8_sdwa v[102:103], v128 src0_sel:WORD_1
	v_cvt_pk_f32_fp8_e32 v[104:105], v129
	v_cvt_pk_f32_fp8_sdwa v[106:107], v129 src0_sel:WORD_1
	v_mfma_f32_4x4x1_16b_f32 v[194:197], v92, v100, v[194:197]
	v_mfma_f32_4x4x1_16b_f32 v[198:201], v92, v101, v[198:201]
	v_mfma_f32_4x4x1_16b_f32 v[202:205], v92, v102, v[202:205]
	v_mfma_f32_4x4x1_16b_f32 v[206:209], v92, v103, v[206:209]
	v_mfma_f32_4x4x1_16b_f32 v[210:213], v92, v104, v[210:213]
	v_mfma_f32_4x4x1_16b_f32 v[214:217], v92, v105, v[214:217]
	v_mfma_f32_4x4x1_16b_f32 v[228:231], v92, v106, v[228:231]
	v_mfma_f32_4x4x1_16b_f32 v[232:235], v92, v107, v[232:235]
	ds_read_b32 v92, v169 offset:1408
	s_waitcnt vmcnt(26) lgkmcnt(1)
	v_cvt_pk_f32_fp8_e32 v[100:101], v130
	v_cvt_pk_f32_fp8_sdwa v[102:103], v130 src0_sel:WORD_1
	v_cvt_pk_f32_fp8_e32 v[104:105], v131
	v_cvt_pk_f32_fp8_sdwa v[106:107], v131 src0_sel:WORD_1
	v_mfma_f32_4x4x1_16b_f32 v[194:197], v93, v100, v[194:197]
	v_mfma_f32_4x4x1_16b_f32 v[198:201], v93, v101, v[198:201]
	v_mfma_f32_4x4x1_16b_f32 v[202:205], v93, v102, v[202:205]
	v_mfma_f32_4x4x1_16b_f32 v[206:209], v93, v103, v[206:209]
	v_mfma_f32_4x4x1_16b_f32 v[210:213], v93, v104, v[210:213]
	v_mfma_f32_4x4x1_16b_f32 v[214:217], v93, v105, v[214:217]
	v_mfma_f32_4x4x1_16b_f32 v[228:231], v93, v106, v[228:231]
	v_mfma_f32_4x4x1_16b_f32 v[232:235], v93, v107, v[232:235]
	ds_read_b32 v93, v169 offset:1472
	s_waitcnt vmcnt(25) lgkmcnt(1)
	v_cvt_pk_f32_fp8_e32 v[100:101], v132
	v_cvt_pk_f32_fp8_sdwa v[102:103], v132 src0_sel:WORD_1
	v_cvt_pk_f32_fp8_e32 v[104:105], v133
	v_cvt_pk_f32_fp8_sdwa v[106:107], v133 src0_sel:WORD_1
	v_mfma_f32_4x4x1_16b_f32 v[194:197], v92, v100, v[194:197]
	v_mfma_f32_4x4x1_16b_f32 v[198:201], v92, v101, v[198:201]
	v_mfma_f32_4x4x1_16b_f32 v[202:205], v92, v102, v[202:205]
	v_mfma_f32_4x4x1_16b_f32 v[206:209], v92, v103, v[206:209]
	v_mfma_f32_4x4x1_16b_f32 v[210:213], v92, v104, v[210:213]
	v_mfma_f32_4x4x1_16b_f32 v[214:217], v92, v105, v[214:217]
	v_mfma_f32_4x4x1_16b_f32 v[228:231], v92, v106, v[228:231]
	v_mfma_f32_4x4x1_16b_f32 v[232:235], v92, v107, v[232:235]
	ds_read_b32 v92, v169 offset:1536
	s_waitcnt vmcnt(24) lgkmcnt(1)
	v_cvt_pk_f32_fp8_e32 v[100:101], v134
	v_cvt_pk_f32_fp8_sdwa v[102:103], v134 src0_sel:WORD_1
	v_cvt_pk_f32_fp8_e32 v[104:105], v135
	v_cvt_pk_f32_fp8_sdwa v[106:107], v135 src0_sel:WORD_1
	v_mfma_f32_4x4x1_16b_f32 v[194:197], v93, v100, v[194:197]
	v_mfma_f32_4x4x1_16b_f32 v[198:201], v93, v101, v[198:201]
	v_mfma_f32_4x4x1_16b_f32 v[202:205], v93, v102, v[202:205]
	v_mfma_f32_4x4x1_16b_f32 v[206:209], v93, v103, v[206:209]
	v_mfma_f32_4x4x1_16b_f32 v[210:213], v93, v104, v[210:213]
	v_mfma_f32_4x4x1_16b_f32 v[214:217], v93, v105, v[214:217]
	v_mfma_f32_4x4x1_16b_f32 v[228:231], v93, v106, v[228:231]
	v_mfma_f32_4x4x1_16b_f32 v[232:235], v93, v107, v[232:235]
	ds_read_b32 v93, v169 offset:1600
	s_waitcnt vmcnt(23) lgkmcnt(1)
; DI void attn_item(const P& p, int b, int kvh, int quad4, char* smem, const AttnPre& pre) {
;     ...
; #pragma unroll 1
;   for (int n0 = 0; n0 < 256; n0 += 64) {
;     uint2 vv[16];
; #pragma unroll
;     for (int u = 0; u < 16; ++u) vv[u] = *(const uint2*)(vb + (size_t)idx[n0 + 4 * u + quad] * 256);
; #pragma unroll
;     for (int u = 0; u < 16; ++u) {
;       const float4 p4 = *(const float4*)(L + (n0 + 4 * u + quad) * 4);
;       const f32x2_t c0 = __builtin_amdgcn_cvt_pk_f32_fp8((int)vv[u].x, false), c1 = __builtin_amdgcn_cvt_pk_f32_fp8((int)vv[u].x, true);
;       const f32x2_t c2 = __builtin_amdgcn_cvt_pk_f32_fp8((int)vv[u].y, false), c3 = __builtin_amdgcn_cvt_pk_f32_fp8((int)vv[u].y, true);
;       const float vf[8] = {c0.x, c0.y, c1.x, c1.y, c2.x, c2.y, c3.x, c3.y};
; #pragma unroll
;       for (int e = 0; e < 8; ++e) {
;         o[0][e] = fmaf(p4.x, vf[e], o[0][e]); o[1][e] = fmaf(p4.y, vf[e], o[1][e]);
;         o[2][e] = fmaf(p4.z, vf[e], o[2][e]); o[3][e] = fmaf(p4.w, vf[e], o[3][e]);
;       }
	v_cvt_pk_f32_fp8_e32 v[100:101], v136
	v_cvt_pk_f32_fp8_sdwa v[102:103], v136 src0_sel:WORD_1
	v_cvt_pk_f32_fp8_e32 v[104:105], v137
	v_cvt_pk_f32_fp8_sdwa v[106:107], v137 src0_sel:WORD_1
	v_mfma_f32_4x4x1_16b_f32 v[194:197], v92, v100, v[194:197]
	v_mfma_f32_4x4x1_16b_f32 v[198:201], v92, v101, v[198:201]
	v_mfma_f32_4x4x1_16b_f32 v[202:205], v92, v102, v[202:205]
	v_mfma_f32_4x4x1_16b_f32 v[206:209], v92, v103, v[206:209]
	v_mfma_f32_4x4x1_16b_f32 v[210:213], v92, v104, v[210:213]
	v_mfma_f32_4x4x1_16b_f32 v[214:217], v92, v105, v[214:217]
	v_mfma_f32_4x4x1_16b_f32 v[228:231], v92, v106, v[228:231]
	v_mfma_f32_4x4x1_16b_f32 v[232:235], v92, v107, v[232:235]
	ds_read_b32 v92, v169 offset:1664
	s_waitcnt vmcnt(22) lgkmcnt(1)
	v_cvt_pk_f32_fp8_e32 v[100:101], v138
	v_cvt_pk_f32_fp8_sdwa v[102:103], v138 src0_sel:WORD_1
	v_cvt_pk_f32_fp8_e32 v[104:105], v139
	v_cvt_pk_f32_fp8_sdwa v[106:107], v139 src0_sel:WORD_1
	v_mfma_f32_4x4x1_16b_f32 v[194:197], v93, v100, v[194:197]
	v_mfma_f32_4x4x1_16b_f32 v[198:201], v93, v101, v[198:201]
	v_mfma_f32_4x4x1_16b_f32 v[202:205], v93, v102, v[202:205]
	v_mfma_f32_4x4x1_16b_f32 v[206:209], v93, v103, v[206:209]
	v_mfma_f32_4x4x1_16b_f32 v[210:213], v93, v104, v[210:213]
	v_mfma_f32_4x4x1_16b_f32 v[214:217], v93, v105, v[214:217]
	v_mfma_f32_4x4x1_16b_f32 v[228:231], v93, v106, v[228:231]
	v_mfma_f32_4x4x1_16b_f32 v[232:235], v93, v107, v[232:235]
	ds_read_b32 v93, v169 offset:1728
	s_waitcnt vmcnt(21) lgkmcnt(1)
	v_cvt_pk_f32_fp8_e32 v[100:101], v140
	v_cvt_pk_f32_fp8_sdwa v[102:103], v140 src0_sel:WORD_1
	v_cvt_pk_f32_fp8_e32 v[104:105], v141
	v_cvt_pk_f32_fp8_sdwa v[106:107], v141 src0_sel:WORD_1
	v_mfma_f32_4x4x1_16b_f32 v[194:197], v92, v100, v[194:197]
	v_mfma_f32_4x4x1_16b_f32 v[198:201], v92, v101, v[198:201]
	v_mfma_f32_4x4x1_16b_f32 v[202:205], v92, v102, v[202:205]
	v_mfma_f32_4x4x1_16b_f32 v[206:209], v92, v103, v[206:209]
	v_mfma_f32_4x4x1_16b_f32 v[210:213], v92, v104, v[210:213]
	v_mfma_f32_4x4x1_16b_f32 v[214:217], v92, v105, v[214:217]
	v_mfma_f32_4x4x1_16b_f32 v[228:231], v92, v106, v[228:231]
	v_mfma_f32_4x4x1_16b_f32 v[232:235], v92, v107, v[232:235]
	ds_read_b32 v92, v169 offset:1792
	s_waitcnt vmcnt(20) lgkmcnt(1)
	v_cvt_pk_f32_fp8_e32 v[100:101], v142
	v_cvt_pk_f32_fp8_sdwa v[102:103], v142 src0_sel:WORD_1
	v_cvt_pk_f32_fp8_e32 v[104:105], v143
	v_cvt_pk_f32_fp8_sdwa v[106:107], v143 src0_sel:WORD_1
	v_mfma_f32_4x4x1_16b_f32 v[194:197], v93, v100, v[194:197]
	v_mfma_f32_4x4x1_16b_f32 v[198:201], v93, v101, v[198:201]
	v_mfma_f32_4x4x1_16b_f32 v[202:205], v93, v102, v[202:205]
	v_mfma_f32_4x4x1_16b_f32 v[206:209], v93, v103, v[206:209]
	v_mfma_f32_4x4x1_16b_f32 v[210:213], v93, v104, v[210:213]
	v_mfma_f32_4x4x1_16b_f32 v[214:217], v93, v105, v[214:217]
	v_mfma_f32_4x4x1_16b_f32 v[228:231], v93, v106, v[228:231]
	v_mfma_f32_4x4x1_16b_f32 v[232:235], v93, v107, v[232:235]
	ds_read_b32 v93, v169 offset:1856
	s_waitcnt vmcnt(19) lgkmcnt(1)
	v_cvt_pk_f32_fp8_e32 v[100:101], v144
	v_cvt_pk_f32_fp8_sdwa v[102:103], v144 src0_sel:WORD_1
	v_cvt_pk_f32_fp8_e32 v[104:105], v145
	v_cvt_pk_f32_fp8_sdwa v[106:107], v145 src0_sel:WORD_1
	v_mfma_f32_4x4x1_16b_f32 v[194:197], v92, v100, v[194:197]
	v_mfma_f32_4x4x1_16b_f32 v[198:201], v92, v101, v[198:201]
	v_mfma_f32_4x4x1_16b_f32 v[202:205], v92, v102, v[202:205]
	v_mfma_f32_4x4x1_16b_f32 v[206:209], v92, v103, v[206:209]
	v_mfma_f32_4x4x1_16b_f32 v[210:213], v92, v104, v[210:213]
	v_mfma_f32_4x4x1_16b_f32 v[214:217], v92, v105, v[214:217]
	v_mfma_f32_4x4x1_16b_f32 v[228:231], v92, v106, v[228:231]
	v_mfma_f32_4x4x1_16b_f32 v[232:235], v92, v107, v[232:235]
	ds_read_b32 v92, v169 offset:1920
	s_waitcnt vmcnt(18) lgkmcnt(1)
	v_cvt_pk_f32_fp8_e32 v[100:101], v146
	v_cvt_pk_f32_fp8_sdwa v[102:103], v146 src0_sel:WORD_1
	v_cvt_pk_f32_fp8_e32 v[104:105], v147
	v_cvt_pk_f32_fp8_sdwa v[106:107], v147 src0_sel:WORD_1
	v_mfma_f32_4x4x1_16b_f32 v[194:197], v93, v100, v[194:197]
	v_mfma_f32_4x4x1_16b_f32 v[198:201], v93, v101, v[198:201]
	v_mfma_f32_4x4x1_16b_f32 v[202:205], v93, v102, v[202:205]
	v_mfma_f32_4x4x1_16b_f32 v[206:209], v93, v103, v[206:209]
	v_mfma_f32_4x4x1_16b_f32 v[210:213], v93, v104, v[210:213]
	v_mfma_f32_4x4x1_16b_f32 v[214:217], v93, v105, v[214:217]
	v_mfma_f32_4x4x1_16b_f32 v[228:231], v93, v106, v[228:231]
	v_mfma_f32_4x4x1_16b_f32 v[232:235], v93, v107, v[232:235]
	ds_read_b32 v93, v169 offset:1984
	s_waitcnt vmcnt(17) lgkmcnt(1)
	v_cvt_pk_f32_fp8_e32 v[100:101], v148
	v_cvt_pk_f32_fp8_sdwa v[102:103], v148 src0_sel:WORD_1
	v_cvt_pk_f32_fp8_e32 v[104:105], v149
	v_cvt_pk_f32_fp8_sdwa v[106:107], v149 src0_sel:WORD_1
	v_mfma_f32_4x4x1_16b_f32 v[194:197], v92, v100, v[194:197]
	v_mfma_f32_4x4x1_16b_f32 v[198:201], v92, v101, v[198:201]
	v_mfma_f32_4x4x1_16b_f32 v[202:205], v92, v102, v[202:205]
	v_mfma_f32_4x4x1_16b_f32 v[206:209], v92, v103, v[206:209]
	v_mfma_f32_4x4x1_16b_f32 v[210:213], v92, v104, v[210:213]
	v_mfma_f32_4x4x1_16b_f32 v[214:217], v92, v105, v[214:217]
	v_mfma_f32_4x4x1_16b_f32 v[228:231], v92, v106, v[228:231]
	v_mfma_f32_4x4x1_16b_f32 v[232:235], v92, v107, v[232:235]
	ds_read_b32 v92, v169 offset:2048
	s_waitcnt vmcnt(16) lgkmcnt(1)
; DI void attn_item(const P& p, int b, int kvh, int quad4, char* smem, const AttnPre& pre) {
;     ...
; #pragma unroll 1
;   for (int n0 = 0; n0 < 256; n0 += 64) {
;     uint2 vv[16];
; #pragma unroll
;     for (int u = 0; u < 16; ++u) vv[u] = *(const uint2*)(vb + (size_t)idx[n0 + 4 * u + quad] * 256);
; #pragma unroll
;     for (int u = 0; u < 16; ++u) {
;       const float4 p4 = *(const float4*)(L + (n0 + 4 * u + quad) * 4);
;       const f32x2_t c0 = __builtin_amdgcn_cvt_pk_f32_fp8((int)vv[u].x, false), c1 = __builtin_amdgcn_cvt_pk_f32_fp8((int)vv[u].x, true);
;       const f32x2_t c2 = __builtin_amdgcn_cvt_pk_f32_fp8((int)vv[u].y, false), c3 = __builtin_amdgcn_cvt_pk_f32_fp8((int)vv[u].y, true);
;       const float vf[8] = {c0.x, c0.y, c1.x, c1.y, c2.x, c2.y, c3.x, c3.y};
; #pragma unroll
;       for (int e = 0; e < 8; ++e) {
;         o[0][e] = fmaf(p4.x, vf[e], o[0][e]); o[1][e] = fmaf(p4.y, vf[e], o[1][e]);
;         o[2][e] = fmaf(p4.z, vf[e], o[2][e]); o[3][e] = fmaf(p4.w, vf[e], o[3][e]);
;       }
	v_cvt_pk_f32_fp8_e32 v[100:101], v150
	v_cvt_pk_f32_fp8_sdwa v[102:103], v150 src0_sel:WORD_1
	v_cvt_pk_f32_fp8_e32 v[104:105], v151
	v_cvt_pk_f32_fp8_sdwa v[106:107], v151 src0_sel:WORD_1
	v_mfma_f32_4x4x1_16b_f32 v[194:197], v93, v100, v[194:197]
	v_mfma_f32_4x4x1_16b_f32 v[198:201], v93, v101, v[198:201]
	v_mfma_f32_4x4x1_16b_f32 v[202:205], v93, v102, v[202:205]
	v_mfma_f32_4x4x1_16b_f32 v[206:209], v93, v103, v[206:209]
	v_mfma_f32_4x4x1_16b_f32 v[210:213], v93, v104, v[210:213]
	v_mfma_f32_4x4x1_16b_f32 v[214:217], v93, v105, v[214:217]
	v_mfma_f32_4x4x1_16b_f32 v[228:231], v93, v106, v[228:231]
	v_mfma_f32_4x4x1_16b_f32 v[232:235], v93, v107, v[232:235]
	ds_read2_b32 v[152:153], v86 offset0:192 offset1:196
	ds_read2_b32 v[154:155], v86 offset0:200 offset1:204
	ds_read2_b32 v[156:157], v86 offset0:208 offset1:212
	ds_read2_b32 v[158:159], v86 offset0:216 offset1:220
	ds_read2_b32 v[160:161], v86 offset0:224 offset1:228
	ds_read2_b32 v[162:163], v86 offset0:232 offset1:236
	ds_read2_b32 v[164:165], v86 offset0:240 offset1:244
	ds_read2_b32 v[166:167], v86 offset0:248 offset1:252
	s_waitcnt lgkmcnt(0)
	v_lshl_add_u32 v152, v152, 8, v168
	v_lshl_add_u32 v153, v153, 8, v168
	v_lshl_add_u32 v154, v154, 8, v168
	v_lshl_add_u32 v155, v155, 8, v168
	v_lshl_add_u32 v156, v156, 8, v168
	v_lshl_add_u32 v157, v157, 8, v168
	v_lshl_add_u32 v158, v158, 8, v168
	v_lshl_add_u32 v159, v159, 8, v168
	v_lshl_add_u32 v160, v160, 8, v168
	v_lshl_add_u32 v161, v161, 8, v168
	v_lshl_add_u32 v162, v162, 8, v168
	v_lshl_add_u32 v163, v163, 8, v168
	v_lshl_add_u32 v164, v164, 8, v168
	v_lshl_add_u32 v165, v165, 8, v168
	v_lshl_add_u32 v166, v166, 8, v168
	v_lshl_add_u32 v167, v167, 8, v168
	global_load_dwordx2 v[120:121], v152, s[6:7]
	global_load_dwordx2 v[122:123], v153, s[6:7]
	global_load_dwordx2 v[124:125], v154, s[6:7]
	global_load_dwordx2 v[126:127], v155, s[6:7]
	global_load_dwordx2 v[128:129], v156, s[6:7]
	global_load_dwordx2 v[130:131], v157, s[6:7]
	global_load_dwordx2 v[132:133], v158, s[6:7]
	global_load_dwordx2 v[134:135], v159, s[6:7]
	global_load_dwordx2 v[136:137], v160, s[6:7]
	global_load_dwordx2 v[138:139], v161, s[6:7]
	global_load_dwordx2 v[140:141], v162, s[6:7]
	global_load_dwordx2 v[142:143], v163, s[6:7]
	global_load_dwordx2 v[144:145], v164, s[6:7]
	global_load_dwordx2 v[146:147], v165, s[6:7]
	global_load_dwordx2 v[148:149], v166, s[6:7]
	global_load_dwordx2 v[150:151], v167, s[6:7]
	ds_read_b32 v93, v169 offset:2112
	s_waitcnt vmcnt(31) lgkmcnt(1)
	v_cvt_pk_f32_fp8_e32 v[100:101], v50
	v_cvt_pk_f32_fp8_sdwa v[102:103], v50 src0_sel:WORD_1
	v_cvt_pk_f32_fp8_e32 v[104:105], v51
	v_cvt_pk_f32_fp8_sdwa v[106:107], v51 src0_sel:WORD_1
	v_mfma_f32_4x4x1_16b_f32 v[194:197], v92, v100, v[194:197]
	v_mfma_f32_4x4x1_16b_f32 v[198:201], v92, v101, v[198:201]
	v_mfma_f32_4x4x1_16b_f32 v[202:205], v92, v102, v[202:205]
	v_mfma_f32_4x4x1_16b_f32 v[206:209], v92, v103, v[206:209]
	v_mfma_f32_4x4x1_16b_f32 v[210:213], v92, v104, v[210:213]
	v_mfma_f32_4x4x1_16b_f32 v[214:217], v92, v105, v[214:217]
	v_mfma_f32_4x4x1_16b_f32 v[228:231], v92, v106, v[228:231]
	v_mfma_f32_4x4x1_16b_f32 v[232:235], v92, v107, v[232:235]
	ds_read_b32 v92, v169 offset:2176
	s_waitcnt vmcnt(30) lgkmcnt(1)
	v_cvt_pk_f32_fp8_e32 v[100:101], v52
	v_cvt_pk_f32_fp8_sdwa v[102:103], v52 src0_sel:WORD_1
	v_cvt_pk_f32_fp8_e32 v[104:105], v53
	v_cvt_pk_f32_fp8_sdwa v[106:107], v53 src0_sel:WORD_1
	v_mfma_f32_4x4x1_16b_f32 v[194:197], v93, v100, v[194:197]
	v_mfma_f32_4x4x1_16b_f32 v[198:201], v93, v101, v[198:201]
	v_mfma_f32_4x4x1_16b_f32 v[202:205], v93, v102, v[202:205]
	v_mfma_f32_4x4x1_16b_f32 v[206:209], v93, v103, v[206:209]
	v_mfma_f32_4x4x1_16b_f32 v[210:213], v93, v104, v[210:213]
	v_mfma_f32_4x4x1_16b_f32 v[214:217], v93, v105, v[214:217]
	v_mfma_f32_4x4x1_16b_f32 v[228:231], v93, v106, v[228:231]
	v_mfma_f32_4x4x1_16b_f32 v[232:235], v93, v107, v[232:235]
	ds_read_b32 v93, v169 offset:2240
	s_waitcnt vmcnt(29) lgkmcnt(1)
	v_cvt_pk_f32_fp8_e32 v[100:101], v54
	v_cvt_pk_f32_fp8_sdwa v[102:103], v54 src0_sel:WORD_1
	v_cvt_pk_f32_fp8_e32 v[104:105], v55
	v_cvt_pk_f32_fp8_sdwa v[106:107], v55 src0_sel:WORD_1
	v_mfma_f32_4x4x1_16b_f32 v[194:197], v92, v100, v[194:197]
	v_mfma_f32_4x4x1_16b_f32 v[198:201], v92, v101, v[198:201]
	v_mfma_f32_4x4x1_16b_f32 v[202:205], v92, v102, v[202:205]
	v_mfma_f32_4x4x1_16b_f32 v[206:209], v92, v103, v[206:209]
	v_mfma_f32_4x4x1_16b_f32 v[210:213], v92, v104, v[210:213]
	v_mfma_f32_4x4x1_16b_f32 v[214:217], v92, v105, v[214:217]
	v_mfma_f32_4x4x1_16b_f32 v[228:231], v92, v106, v[228:231]
	v_mfma_f32_4x4x1_16b_f32 v[232:235], v92, v107, v[232:235]
	ds_read_b32 v92, v169 offset:2304
	s_waitcnt vmcnt(28) lgkmcnt(1)
	v_cvt_pk_f32_fp8_e32 v[100:101], v56
	v_cvt_pk_f32_fp8_sdwa v[102:103], v56 src0_sel:WORD_1
	v_cvt_pk_f32_fp8_e32 v[104:105], v57
	v_cvt_pk_f32_fp8_sdwa v[106:107], v57 src0_sel:WORD_1
	v_mfma_f32_4x4x1_16b_f32 v[194:197], v93, v100, v[194:197]
	v_mfma_f32_4x4x1_16b_f32 v[198:201], v93, v101, v[198:201]
	v_mfma_f32_4x4x1_16b_f32 v[202:205], v93, v102, v[202:205]
	v_mfma_f32_4x4x1_16b_f32 v[206:209], v93, v103, v[206:209]
	v_mfma_f32_4x4x1_16b_f32 v[210:213], v93, v104, v[210:213]
	v_mfma_f32_4x4x1_16b_f32 v[214:217], v93, v105, v[214:217]
	v_mfma_f32_4x4x1_16b_f32 v[228:231], v93, v106, v[228:231]
	v_mfma_f32_4x4x1_16b_f32 v[232:235], v93, v107, v[232:235]
	ds_read_b32 v93, v169 offset:2368
	s_waitcnt vmcnt(27) lgkmcnt(1)
; DI void attn_item(const P& p, int b, int kvh, int quad4, char* smem, const AttnPre& pre) {
;     ...
; #pragma unroll 1
;   for (int n0 = 0; n0 < 256; n0 += 64) {
;     uint2 vv[16];
; #pragma unroll
;     for (int u = 0; u < 16; ++u) vv[u] = *(const uint2*)(vb + (size_t)idx[n0 + 4 * u + quad] * 256);
; #pragma unroll
;     for (int u = 0; u < 16; ++u) {
;       const float4 p4 = *(const float4*)(L + (n0 + 4 * u + quad) * 4);
;       const f32x2_t c0 = __builtin_amdgcn_cvt_pk_f32_fp8((int)vv[u].x, false), c1 = __builtin_amdgcn_cvt_pk_f32_fp8((int)vv[u].x, true);
;       const f32x2_t c2 = __builtin_amdgcn_cvt_pk_f32_fp8((int)vv[u].y, false), c3 = __builtin_amdgcn_cvt_pk_f32_fp8((int)vv[u].y, true);
;       const float vf[8] = {c0.x, c0.y, c1.x, c1.y, c2.x, c2.y, c3.x, c3.y};
; #pragma unroll
;       for (int e = 0; e < 8; ++e) {
;         o[0][e] = fmaf(p4.x, vf[e], o[0][e]); o[1][e] = fmaf(p4.y, vf[e], o[1][e]);
;         o[2][e] = fmaf(p4.z, vf[e], o[2][e]); o[3][e] = fmaf(p4.w, vf[e], o[3][e]);
;       }
	v_cvt_pk_f32_fp8_e32 v[100:101], v58
	v_cvt_pk_f32_fp8_sdwa v[102:103], v58 src0_sel:WORD_1
	v_cvt_pk_f32_fp8_e32 v[104:105], v59
	v_cvt_pk_f32_fp8_sdwa v[106:107], v59 src0_sel:WORD_1
	v_mfma_f32_4x4x1_16b_f32 v[194:197], v92, v100, v[194:197]
	v_mfma_f32_4x4x1_16b_f32 v[198:201], v92, v101, v[198:201]
	v_mfma_f32_4x4x1_16b_f32 v[202:205], v92, v102, v[202:205]
	v_mfma_f32_4x4x1_16b_f32 v[206:209], v92, v103, v[206:209]
	v_mfma_f32_4x4x1_16b_f32 v[210:213], v92, v104, v[210:213]
	v_mfma_f32_4x4x1_16b_f32 v[214:217], v92, v105, v[214:217]
	v_mfma_f32_4x4x1_16b_f32 v[228:231], v92, v106, v[228:231]
	v_mfma_f32_4x4x1_16b_f32 v[232:235], v92, v107, v[232:235]
	ds_read_b32 v92, v169 offset:2432
	s_waitcnt vmcnt(26) lgkmcnt(1)
	v_cvt_pk_f32_fp8_e32 v[100:101], v60
	v_cvt_pk_f32_fp8_sdwa v[102:103], v60 src0_sel:WORD_1
	v_cvt_pk_f32_fp8_e32 v[104:105], v61
	v_cvt_pk_f32_fp8_sdwa v[106:107], v61 src0_sel:WORD_1
	v_mfma_f32_4x4x1_16b_f32 v[194:197], v93, v100, v[194:197]
	v_mfma_f32_4x4x1_16b_f32 v[198:201], v93, v101, v[198:201]
	v_mfma_f32_4x4x1_16b_f32 v[202:205], v93, v102, v[202:205]
	v_mfma_f32_4x4x1_16b_f32 v[206:209], v93, v103, v[206:209]
	v_mfma_f32_4x4x1_16b_f32 v[210:213], v93, v104, v[210:213]
	v_mfma_f32_4x4x1_16b_f32 v[214:217], v93, v105, v[214:217]
	v_mfma_f32_4x4x1_16b_f32 v[228:231], v93, v106, v[228:231]
	v_mfma_f32_4x4x1_16b_f32 v[232:235], v93, v107, v[232:235]
	ds_read_b32 v93, v169 offset:2496
	s_waitcnt vmcnt(25) lgkmcnt(1)
	v_cvt_pk_f32_fp8_e32 v[100:101], v62
	v_cvt_pk_f32_fp8_sdwa v[102:103], v62 src0_sel:WORD_1
	v_cvt_pk_f32_fp8_e32 v[104:105], v63
	v_cvt_pk_f32_fp8_sdwa v[106:107], v63 src0_sel:WORD_1
	v_mfma_f32_4x4x1_16b_f32 v[194:197], v92, v100, v[194:197]
	v_mfma_f32_4x4x1_16b_f32 v[198:201], v92, v101, v[198:201]
	v_mfma_f32_4x4x1_16b_f32 v[202:205], v92, v102, v[202:205]
	v_mfma_f32_4x4x1_16b_f32 v[206:209], v92, v103, v[206:209]
	v_mfma_f32_4x4x1_16b_f32 v[210:213], v92, v104, v[210:213]
	v_mfma_f32_4x4x1_16b_f32 v[214:217], v92, v105, v[214:217]
	v_mfma_f32_4x4x1_16b_f32 v[228:231], v92, v106, v[228:231]
	v_mfma_f32_4x4x1_16b_f32 v[232:235], v92, v107, v[232:235]
	ds_read_b32 v92, v169 offset:2560
	s_waitcnt vmcnt(24) lgkmcnt(1)
	v_cvt_pk_f32_fp8_e32 v[100:101], v64
	v_cvt_pk_f32_fp8_sdwa v[102:103], v64 src0_sel:WORD_1
	v_cvt_pk_f32_fp8_e32 v[104:105], v65
	v_cvt_pk_f32_fp8_sdwa v[106:107], v65 src0_sel:WORD_1
	v_mfma_f32_4x4x1_16b_f32 v[194:197], v93, v100, v[194:197]
	v_mfma_f32_4x4x1_16b_f32 v[198:201], v93, v101, v[198:201]
	v_mfma_f32_4x4x1_16b_f32 v[202:205], v93, v102, v[202:205]
	v_mfma_f32_4x4x1_16b_f32 v[206:209], v93, v103, v[206:209]
	v_mfma_f32_4x4x1_16b_f32 v[210:213], v93, v104, v[210:213]
	v_mfma_f32_4x4x1_16b_f32 v[214:217], v93, v105, v[214:217]
	v_mfma_f32_4x4x1_16b_f32 v[228:231], v93, v106, v[228:231]
	v_mfma_f32_4x4x1_16b_f32 v[232:235], v93, v107, v[232:235]
	ds_read_b32 v93, v169 offset:2624
	s_waitcnt vmcnt(23) lgkmcnt(1)
	v_cvt_pk_f32_fp8_e32 v[100:101], v66
	v_cvt_pk_f32_fp8_sdwa v[102:103], v66 src0_sel:WORD_1
	v_cvt_pk_f32_fp8_e32 v[104:105], v67
	v_cvt_pk_f32_fp8_sdwa v[106:107], v67 src0_sel:WORD_1
	v_mfma_f32_4x4x1_16b_f32 v[194:197], v92, v100, v[194:197]
	v_mfma_f32_4x4x1_16b_f32 v[198:201], v92, v101, v[198:201]
	v_mfma_f32_4x4x1_16b_f32 v[202:205], v92, v102, v[202:205]
	v_mfma_f32_4x4x1_16b_f32 v[206:209], v92, v103, v[206:209]
	v_mfma_f32_4x4x1_16b_f32 v[210:213], v92, v104, v[210:213]
	v_mfma_f32_4x4x1_16b_f32 v[214:217], v92, v105, v[214:217]
	v_mfma_f32_4x4x1_16b_f32 v[228:231], v92, v106, v[228:231]
	v_mfma_f32_4x4x1_16b_f32 v[232:235], v92, v107, v[232:235]
	ds_read_b32 v92, v169 offset:2688
	s_waitcnt vmcnt(22) lgkmcnt(1)
	v_cvt_pk_f32_fp8_e32 v[100:101], v68
	v_cvt_pk_f32_fp8_sdwa v[102:103], v68 src0_sel:WORD_1
	v_cvt_pk_f32_fp8_e32 v[104:105], v69
	v_cvt_pk_f32_fp8_sdwa v[106:107], v69 src0_sel:WORD_1
	v_mfma_f32_4x4x1_16b_f32 v[194:197], v93, v100, v[194:197]
	v_mfma_f32_4x4x1_16b_f32 v[198:201], v93, v101, v[198:201]
	v_mfma_f32_4x4x1_16b_f32 v[202:205], v93, v102, v[202:205]
	v_mfma_f32_4x4x1_16b_f32 v[206:209], v93, v103, v[206:209]
	v_mfma_f32_4x4x1_16b_f32 v[210:213], v93, v104, v[210:213]
	v_mfma_f32_4x4x1_16b_f32 v[214:217], v93, v105, v[214:217]
	v_mfma_f32_4x4x1_16b_f32 v[228:231], v93, v106, v[228:231]
	v_mfma_f32_4x4x1_16b_f32 v[232:235], v93, v107, v[232:235]
	ds_read_b32 v93, v169 offset:2752
	s_waitcnt vmcnt(21) lgkmcnt(1)
	v_cvt_pk_f32_fp8_e32 v[100:101], v70
	v_cvt_pk_f32_fp8_sdwa v[102:103], v70 src0_sel:WORD_1
	v_cvt_pk_f32_fp8_e32 v[104:105], v71
	v_cvt_pk_f32_fp8_sdwa v[106:107], v71 src0_sel:WORD_1
	v_mfma_f32_4x4x1_16b_f32 v[194:197], v92, v100, v[194:197]
	v_mfma_f32_4x4x1_16b_f32 v[198:201], v92, v101, v[198:201]
	v_mfma_f32_4x4x1_16b_f32 v[202:205], v92, v102, v[202:205]
	v_mfma_f32_4x4x1_16b_f32 v[206:209], v92, v103, v[206:209]
	v_mfma_f32_4x4x1_16b_f32 v[210:213], v92, v104, v[210:213]
	v_mfma_f32_4x4x1_16b_f32 v[214:217], v92, v105, v[214:217]
	v_mfma_f32_4x4x1_16b_f32 v[228:231], v92, v106, v[228:231]
	v_mfma_f32_4x4x1_16b_f32 v[232:235], v92, v107, v[232:235]
	ds_read_b32 v92, v169 offset:2816
	s_waitcnt vmcnt(20) lgkmcnt(1)
	v_cvt_pk_f32_fp8_e32 v[100:101], v72
	v_cvt_pk_f32_fp8_sdwa v[102:103], v72 src0_sel:WORD_1
	v_cvt_pk_f32_fp8_e32 v[104:105], v73
	v_cvt_pk_f32_fp8_sdwa v[106:107], v73 src0_sel:WORD_1
	v_mfma_f32_4x4x1_16b_f32 v[194:197], v93, v100, v[194:197]
	v_mfma_f32_4x4x1_16b_f32 v[198:201], v93, v101, v[198:201]
	v_mfma_f32_4x4x1_16b_f32 v[202:205], v93, v102, v[202:205]
	v_mfma_f32_4x4x1_16b_f32 v[206:209], v93, v103, v[206:209]
	v_mfma_f32_4x4x1_16b_f32 v[210:213], v93, v104, v[210:213]
	v_mfma_f32_4x4x1_16b_f32 v[214:217], v93, v105, v[214:217]
	v_mfma_f32_4x4x1_16b_f32 v[228:231], v93, v106, v[228:231]
	v_mfma_f32_4x4x1_16b_f32 v[232:235], v93, v107, v[232:235]
	ds_read_b32 v93, v169 offset:2880
	s_waitcnt vmcnt(19) lgkmcnt(1)
; DI void attn_item(const P& p, int b, int kvh, int quad4, char* smem, const AttnPre& pre) {
;     ...
; #pragma unroll 1
;   for (int n0 = 0; n0 < 256; n0 += 64) {
;     uint2 vv[16];
; #pragma unroll
;     for (int u = 0; u < 16; ++u) vv[u] = *(const uint2*)(vb + (size_t)idx[n0 + 4 * u + quad] * 256);
; #pragma unroll
;     for (int u = 0; u < 16; ++u) {
;       const float4 p4 = *(const float4*)(L + (n0 + 4 * u + quad) * 4);
;       const f32x2_t c0 = __builtin_amdgcn_cvt_pk_f32_fp8((int)vv[u].x, false), c1 = __builtin_amdgcn_cvt_pk_f32_fp8((int)vv[u].x, true);
;       const f32x2_t c2 = __builtin_amdgcn_cvt_pk_f32_fp8((int)vv[u].y, false), c3 = __builtin_amdgcn_cvt_pk_f32_fp8((int)vv[u].y, true);
;       const float vf[8] = {c0.x, c0.y, c1.x, c1.y, c2.x, c2.y, c3.x, c3.y};
; #pragma unroll
;       for (int e = 0; e < 8; ++e) {
;         o[0][e] = fmaf(p4.x, vf[e], o[0][e]); o[1][e] = fmaf(p4.y, vf[e], o[1][e]);
;         o[2][e] = fmaf(p4.z, vf[e], o[2][e]); o[3][e] = fmaf(p4.w, vf[e], o[3][e]);
;       }
	v_cvt_pk_f32_fp8_e32 v[100:101], v74
	v_cvt_pk_f32_fp8_sdwa v[102:103], v74 src0_sel:WORD_1
	v_cvt_pk_f32_fp8_e32 v[104:105], v75
	v_cvt_pk_f32_fp8_sdwa v[106:107], v75 src0_sel:WORD_1
	v_mfma_f32_4x4x1_16b_f32 v[194:197], v92, v100, v[194:197]
	v_mfma_f32_4x4x1_16b_f32 v[198:201], v92, v101, v[198:201]
	v_mfma_f32_4x4x1_16b_f32 v[202:205], v92, v102, v[202:205]
	v_mfma_f32_4x4x1_16b_f32 v[206:209], v92, v103, v[206:209]
	v_mfma_f32_4x4x1_16b_f32 v[210:213], v92, v104, v[210:213]
	v_mfma_f32_4x4x1_16b_f32 v[214:217], v92, v105, v[214:217]
	v_mfma_f32_4x4x1_16b_f32 v[228:231], v92, v106, v[228:231]
	v_mfma_f32_4x4x1_16b_f32 v[232:235], v92, v107, v[232:235]
	ds_read_b32 v92, v169 offset:2944
	s_waitcnt vmcnt(18) lgkmcnt(1)
	v_cvt_pk_f32_fp8_e32 v[100:101], v76
	v_cvt_pk_f32_fp8_sdwa v[102:103], v76 src0_sel:WORD_1
	v_cvt_pk_f32_fp8_e32 v[104:105], v77
	v_cvt_pk_f32_fp8_sdwa v[106:107], v77 src0_sel:WORD_1
	v_mfma_f32_4x4x1_16b_f32 v[194:197], v93, v100, v[194:197]
	v_mfma_f32_4x4x1_16b_f32 v[198:201], v93, v101, v[198:201]
	v_mfma_f32_4x4x1_16b_f32 v[202:205], v93, v102, v[202:205]
	v_mfma_f32_4x4x1_16b_f32 v[206:209], v93, v103, v[206:209]
	v_mfma_f32_4x4x1_16b_f32 v[210:213], v93, v104, v[210:213]
	v_mfma_f32_4x4x1_16b_f32 v[214:217], v93, v105, v[214:217]
	v_mfma_f32_4x4x1_16b_f32 v[228:231], v93, v106, v[228:231]
	v_mfma_f32_4x4x1_16b_f32 v[232:235], v93, v107, v[232:235]
	ds_read_b32 v93, v169 offset:3008
	s_waitcnt vmcnt(17) lgkmcnt(1)
	v_cvt_pk_f32_fp8_e32 v[100:101], v78
	v_cvt_pk_f32_fp8_sdwa v[102:103], v78 src0_sel:WORD_1
	v_cvt_pk_f32_fp8_e32 v[104:105], v79
	v_cvt_pk_f32_fp8_sdwa v[106:107], v79 src0_sel:WORD_1
	v_mfma_f32_4x4x1_16b_f32 v[194:197], v92, v100, v[194:197]
	v_mfma_f32_4x4x1_16b_f32 v[198:201], v92, v101, v[198:201]
	v_mfma_f32_4x4x1_16b_f32 v[202:205], v92, v102, v[202:205]
	v_mfma_f32_4x4x1_16b_f32 v[206:209], v92, v103, v[206:209]
	v_mfma_f32_4x4x1_16b_f32 v[210:213], v92, v104, v[210:213]
	v_mfma_f32_4x4x1_16b_f32 v[214:217], v92, v105, v[214:217]
	v_mfma_f32_4x4x1_16b_f32 v[228:231], v92, v106, v[228:231]
	v_mfma_f32_4x4x1_16b_f32 v[232:235], v92, v107, v[232:235]
	ds_read_b32 v92, v169 offset:3072
	s_waitcnt vmcnt(16) lgkmcnt(1)
	v_cvt_pk_f32_fp8_e32 v[100:101], v80
	v_cvt_pk_f32_fp8_sdwa v[102:103], v80 src0_sel:WORD_1
	v_cvt_pk_f32_fp8_e32 v[104:105], v81
	v_cvt_pk_f32_fp8_sdwa v[106:107], v81 src0_sel:WORD_1
	v_mfma_f32_4x4x1_16b_f32 v[194:197], v93, v100, v[194:197]
	v_mfma_f32_4x4x1_16b_f32 v[198:201], v93, v101, v[198:201]
	v_mfma_f32_4x4x1_16b_f32 v[202:205], v93, v102, v[202:205]
	v_mfma_f32_4x4x1_16b_f32 v[206:209], v93, v103, v[206:209]
	v_mfma_f32_4x4x1_16b_f32 v[210:213], v93, v104, v[210:213]
	v_mfma_f32_4x4x1_16b_f32 v[214:217], v93, v105, v[214:217]
	v_mfma_f32_4x4x1_16b_f32 v[228:231], v93, v106, v[228:231]
	v_mfma_f32_4x4x1_16b_f32 v[232:235], v93, v107, v[232:235]
	ds_read_b32 v93, v169 offset:3136
	s_waitcnt vmcnt(15) lgkmcnt(1)
	v_cvt_pk_f32_fp8_e32 v[100:101], v120
	v_cvt_pk_f32_fp8_sdwa v[102:103], v120 src0_sel:WORD_1
	v_cvt_pk_f32_fp8_e32 v[104:105], v121
	v_cvt_pk_f32_fp8_sdwa v[106:107], v121 src0_sel:WORD_1
	v_mfma_f32_4x4x1_16b_f32 v[194:197], v92, v100, v[194:197]
	v_mfma_f32_4x4x1_16b_f32 v[198:201], v92, v101, v[198:201]
	v_mfma_f32_4x4x1_16b_f32 v[202:205], v92, v102, v[202:205]
	v_mfma_f32_4x4x1_16b_f32 v[206:209], v92, v103, v[206:209]
	v_mfma_f32_4x4x1_16b_f32 v[210:213], v92, v104, v[210:213]
	v_mfma_f32_4x4x1_16b_f32 v[214:217], v92, v105, v[214:217]
	v_mfma_f32_4x4x1_16b_f32 v[228:231], v92, v106, v[228:231]
	v_mfma_f32_4x4x1_16b_f32 v[232:235], v92, v107, v[232:235]
	ds_read_b32 v92, v169 offset:3200
	s_waitcnt vmcnt(14) lgkmcnt(1)
	v_cvt_pk_f32_fp8_e32 v[100:101], v122
	v_cvt_pk_f32_fp8_sdwa v[102:103], v122 src0_sel:WORD_1
	v_cvt_pk_f32_fp8_e32 v[104:105], v123
	v_cvt_pk_f32_fp8_sdwa v[106:107], v123 src0_sel:WORD_1
	v_mfma_f32_4x4x1_16b_f32 v[194:197], v93, v100, v[194:197]
	v_mfma_f32_4x4x1_16b_f32 v[198:201], v93, v101, v[198:201]
	v_mfma_f32_4x4x1_16b_f32 v[202:205], v93, v102, v[202:205]
	v_mfma_f32_4x4x1_16b_f32 v[206:209], v93, v103, v[206:209]
	v_mfma_f32_4x4x1_16b_f32 v[210:213], v93, v104, v[210:213]
	v_mfma_f32_4x4x1_16b_f32 v[214:217], v93, v105, v[214:217]
	v_mfma_f32_4x4x1_16b_f32 v[228:231], v93, v106, v[228:231]
	v_mfma_f32_4x4x1_16b_f32 v[232:235], v93, v107, v[232:235]
	ds_read_b32 v93, v169 offset:3264
	s_waitcnt vmcnt(13) lgkmcnt(1)
	v_cvt_pk_f32_fp8_e32 v[100:101], v124
	v_cvt_pk_f32_fp8_sdwa v[102:103], v124 src0_sel:WORD_1
	v_cvt_pk_f32_fp8_e32 v[104:105], v125
	v_cvt_pk_f32_fp8_sdwa v[106:107], v125 src0_sel:WORD_1
	v_mfma_f32_4x4x1_16b_f32 v[194:197], v92, v100, v[194:197]
	v_mfma_f32_4x4x1_16b_f32 v[198:201], v92, v101, v[198:201]
	v_mfma_f32_4x4x1_16b_f32 v[202:205], v92, v102, v[202:205]
	v_mfma_f32_4x4x1_16b_f32 v[206:209], v92, v103, v[206:209]
	v_mfma_f32_4x4x1_16b_f32 v[210:213], v92, v104, v[210:213]
	v_mfma_f32_4x4x1_16b_f32 v[214:217], v92, v105, v[214:217]
	v_mfma_f32_4x4x1_16b_f32 v[228:231], v92, v106, v[228:231]
	v_mfma_f32_4x4x1_16b_f32 v[232:235], v92, v107, v[232:235]
	ds_read_b32 v92, v169 offset:3328
	s_waitcnt vmcnt(12) lgkmcnt(1)
	v_cvt_pk_f32_fp8_e32 v[100:101], v126
	v_cvt_pk_f32_fp8_sdwa v[102:103], v126 src0_sel:WORD_1
	v_cvt_pk_f32_fp8_e32 v[104:105], v127
	v_cvt_pk_f32_fp8_sdwa v[106:107], v127 src0_sel:WORD_1
	v_mfma_f32_4x4x1_16b_f32 v[194:197], v93, v100, v[194:197]
	v_mfma_f32_4x4x1_16b_f32 v[198:201], v93, v101, v[198:201]
	v_mfma_f32_4x4x1_16b_f32 v[202:205], v93, v102, v[202:205]
	v_mfma_f32_4x4x1_16b_f32 v[206:209], v93, v103, v[206:209]
	v_mfma_f32_4x4x1_16b_f32 v[210:213], v93, v104, v[210:213]
	v_mfma_f32_4x4x1_16b_f32 v[214:217], v93, v105, v[214:217]
	v_mfma_f32_4x4x1_16b_f32 v[228:231], v93, v106, v[228:231]
	v_mfma_f32_4x4x1_16b_f32 v[232:235], v93, v107, v[232:235]
	ds_read_b32 v93, v169 offset:3392
	s_waitcnt vmcnt(11) lgkmcnt(1)
; DI void attn_item(const P& p, int b, int kvh, int quad4, char* smem, const AttnPre& pre) {
;     ...
; #pragma unroll 1
;   for (int n0 = 0; n0 < 256; n0 += 64) {
;     uint2 vv[16];
; #pragma unroll
;     for (int u = 0; u < 16; ++u) vv[u] = *(const uint2*)(vb + (size_t)idx[n0 + 4 * u + quad] * 256);
; #pragma unroll
;     for (int u = 0; u < 16; ++u) {
;       const float4 p4 = *(const float4*)(L + (n0 + 4 * u + quad) * 4);
;       const f32x2_t c0 = __builtin_amdgcn_cvt_pk_f32_fp8((int)vv[u].x, false), c1 = __builtin_amdgcn_cvt_pk_f32_fp8((int)vv[u].x, true);
;       const f32x2_t c2 = __builtin_amdgcn_cvt_pk_f32_fp8((int)vv[u].y, false), c3 = __builtin_amdgcn_cvt_pk_f32_fp8((int)vv[u].y, true);
;       const float vf[8] = {c0.x, c0.y, c1.x, c1.y, c2.x, c2.y, c3.x, c3.y};
; #pragma unroll
;       for (int e = 0; e < 8; ++e) {
;         o[0][e] = fmaf(p4.x, vf[e], o[0][e]); o[1][e] = fmaf(p4.y, vf[e], o[1][e]);
;         o[2][e] = fmaf(p4.z, vf[e], o[2][e]); o[3][e] = fmaf(p4.w, vf[e], o[3][e]);
;       }
	v_cvt_pk_f32_fp8_e32 v[100:101], v128
	v_cvt_pk_f32_fp8_sdwa v[102:103], v128 src0_sel:WORD_1
	v_cvt_pk_f32_fp8_e32 v[104:105], v129
	v_cvt_pk_f32_fp8_sdwa v[106:107], v129 src0_sel:WORD_1
	v_mfma_f32_4x4x1_16b_f32 v[194:197], v92, v100, v[194:197]
	v_mfma_f32_4x4x1_16b_f32 v[198:201], v92, v101, v[198:201]
	v_mfma_f32_4x4x1_16b_f32 v[202:205], v92, v102, v[202:205]
	v_mfma_f32_4x4x1_16b_f32 v[206:209], v92, v103, v[206:209]
	v_mfma_f32_4x4x1_16b_f32 v[210:213], v92, v104, v[210:213]
	v_mfma_f32_4x4x1_16b_f32 v[214:217], v92, v105, v[214:217]
	v_mfma_f32_4x4x1_16b_f32 v[228:231], v92, v106, v[228:231]
	v_mfma_f32_4x4x1_16b_f32 v[232:235], v92, v107, v[232:235]
	ds_read_b32 v92, v169 offset:3456
	s_waitcnt vmcnt(10) lgkmcnt(1)
	v_cvt_pk_f32_fp8_e32 v[100:101], v130
	v_cvt_pk_f32_fp8_sdwa v[102:103], v130 src0_sel:WORD_1
	v_cvt_pk_f32_fp8_e32 v[104:105], v131
	v_cvt_pk_f32_fp8_sdwa v[106:107], v131 src0_sel:WORD_1
	v_mfma_f32_4x4x1_16b_f32 v[194:197], v93, v100, v[194:197]
	v_mfma_f32_4x4x1_16b_f32 v[198:201], v93, v101, v[198:201]
	v_mfma_f32_4x4x1_16b_f32 v[202:205], v93, v102, v[202:205]
	v_mfma_f32_4x4x1_16b_f32 v[206:209], v93, v103, v[206:209]
	v_mfma_f32_4x4x1_16b_f32 v[210:213], v93, v104, v[210:213]
	v_mfma_f32_4x4x1_16b_f32 v[214:217], v93, v105, v[214:217]
	v_mfma_f32_4x4x1_16b_f32 v[228:231], v93, v106, v[228:231]
	v_mfma_f32_4x4x1_16b_f32 v[232:235], v93, v107, v[232:235]
	ds_read_b32 v93, v169 offset:3520
	s_waitcnt vmcnt(9) lgkmcnt(1)
	v_cvt_pk_f32_fp8_e32 v[100:101], v132
	v_cvt_pk_f32_fp8_sdwa v[102:103], v132 src0_sel:WORD_1
	v_cvt_pk_f32_fp8_e32 v[104:105], v133
	v_cvt_pk_f32_fp8_sdwa v[106:107], v133 src0_sel:WORD_1
	v_mfma_f32_4x4x1_16b_f32 v[194:197], v92, v100, v[194:197]
	v_mfma_f32_4x4x1_16b_f32 v[198:201], v92, v101, v[198:201]
	v_mfma_f32_4x4x1_16b_f32 v[202:205], v92, v102, v[202:205]
	v_mfma_f32_4x4x1_16b_f32 v[206:209], v92, v103, v[206:209]
	v_mfma_f32_4x4x1_16b_f32 v[210:213], v92, v104, v[210:213]
	v_mfma_f32_4x4x1_16b_f32 v[214:217], v92, v105, v[214:217]
	v_mfma_f32_4x4x1_16b_f32 v[228:231], v92, v106, v[228:231]
	v_mfma_f32_4x4x1_16b_f32 v[232:235], v92, v107, v[232:235]
	ds_read_b32 v92, v169 offset:3584
	s_waitcnt vmcnt(8) lgkmcnt(1)
	v_cvt_pk_f32_fp8_e32 v[100:101], v134
	v_cvt_pk_f32_fp8_sdwa v[102:103], v134 src0_sel:WORD_1
	v_cvt_pk_f32_fp8_e32 v[104:105], v135
	v_cvt_pk_f32_fp8_sdwa v[106:107], v135 src0_sel:WORD_1
	v_mfma_f32_4x4x1_16b_f32 v[194:197], v93, v100, v[194:197]
	v_mfma_f32_4x4x1_16b_f32 v[198:201], v93, v101, v[198:201]
	v_mfma_f32_4x4x1_16b_f32 v[202:205], v93, v102, v[202:205]
	v_mfma_f32_4x4x1_16b_f32 v[206:209], v93, v103, v[206:209]
	v_mfma_f32_4x4x1_16b_f32 v[210:213], v93, v104, v[210:213]
	v_mfma_f32_4x4x1_16b_f32 v[214:217], v93, v105, v[214:217]
	v_mfma_f32_4x4x1_16b_f32 v[228:231], v93, v106, v[228:231]
	v_mfma_f32_4x4x1_16b_f32 v[232:235], v93, v107, v[232:235]
	ds_read_b32 v93, v169 offset:3648
	s_waitcnt vmcnt(7) lgkmcnt(1)
	v_cvt_pk_f32_fp8_e32 v[100:101], v136
	v_cvt_pk_f32_fp8_sdwa v[102:103], v136 src0_sel:WORD_1
	v_cvt_pk_f32_fp8_e32 v[104:105], v137
	v_cvt_pk_f32_fp8_sdwa v[106:107], v137 src0_sel:WORD_1
	v_mfma_f32_4x4x1_16b_f32 v[194:197], v92, v100, v[194:197]
	v_mfma_f32_4x4x1_16b_f32 v[198:201], v92, v101, v[198:201]
	v_mfma_f32_4x4x1_16b_f32 v[202:205], v92, v102, v[202:205]
	v_mfma_f32_4x4x1_16b_f32 v[206:209], v92, v103, v[206:209]
	v_mfma_f32_4x4x1_16b_f32 v[210:213], v92, v104, v[210:213]
	v_mfma_f32_4x4x1_16b_f32 v[214:217], v92, v105, v[214:217]
	v_mfma_f32_4x4x1_16b_f32 v[228:231], v92, v106, v[228:231]
	v_mfma_f32_4x4x1_16b_f32 v[232:235], v92, v107, v[232:235]
	ds_read_b32 v92, v169 offset:3712
	s_waitcnt vmcnt(6) lgkmcnt(1)
	v_cvt_pk_f32_fp8_e32 v[100:101], v138
	v_cvt_pk_f32_fp8_sdwa v[102:103], v138 src0_sel:WORD_1
	v_cvt_pk_f32_fp8_e32 v[104:105], v139
	v_cvt_pk_f32_fp8_sdwa v[106:107], v139 src0_sel:WORD_1
	v_mfma_f32_4x4x1_16b_f32 v[194:197], v93, v100, v[194:197]
	v_mfma_f32_4x4x1_16b_f32 v[198:201], v93, v101, v[198:201]
	v_mfma_f32_4x4x1_16b_f32 v[202:205], v93, v102, v[202:205]
	v_mfma_f32_4x4x1_16b_f32 v[206:209], v93, v103, v[206:209]
	v_mfma_f32_4x4x1_16b_f32 v[210:213], v93, v104, v[210:213]
	v_mfma_f32_4x4x1_16b_f32 v[214:217], v93, v105, v[214:217]
	v_mfma_f32_4x4x1_16b_f32 v[228:231], v93, v106, v[228:231]
	v_mfma_f32_4x4x1_16b_f32 v[232:235], v93, v107, v[232:235]
	ds_read_b32 v93, v169 offset:3776
	s_waitcnt vmcnt(5) lgkmcnt(1)
	v_cvt_pk_f32_fp8_e32 v[100:101], v140
	v_cvt_pk_f32_fp8_sdwa v[102:103], v140 src0_sel:WORD_1
	v_cvt_pk_f32_fp8_e32 v[104:105], v141
	v_cvt_pk_f32_fp8_sdwa v[106:107], v141 src0_sel:WORD_1
	v_mfma_f32_4x4x1_16b_f32 v[194:197], v92, v100, v[194:197]
	v_mfma_f32_4x4x1_16b_f32 v[198:201], v92, v101, v[198:201]
	v_mfma_f32_4x4x1_16b_f32 v[202:205], v92, v102, v[202:205]
	v_mfma_f32_4x4x1_16b_f32 v[206:209], v92, v103, v[206:209]
	v_mfma_f32_4x4x1_16b_f32 v[210:213], v92, v104, v[210:213]
	v_mfma_f32_4x4x1_16b_f32 v[214:217], v92, v105, v[214:217]
	v_mfma_f32_4x4x1_16b_f32 v[228:231], v92, v106, v[228:231]
	v_mfma_f32_4x4x1_16b_f32 v[232:235], v92, v107, v[232:235]
	ds_read_b32 v92, v169 offset:3840
	s_waitcnt vmcnt(4) lgkmcnt(1)
	v_cvt_pk_f32_fp8_e32 v[100:101], v142
	v_cvt_pk_f32_fp8_sdwa v[102:103], v142 src0_sel:WORD_1
	v_cvt_pk_f32_fp8_e32 v[104:105], v143
	v_cvt_pk_f32_fp8_sdwa v[106:107], v143 src0_sel:WORD_1
	v_mfma_f32_4x4x1_16b_f32 v[194:197], v93, v100, v[194:197]
	v_mfma_f32_4x4x1_16b_f32 v[198:201], v93, v101, v[198:201]
	v_mfma_f32_4x4x1_16b_f32 v[202:205], v93, v102, v[202:205]
	v_mfma_f32_4x4x1_16b_f32 v[206:209], v93, v103, v[206:209]
	v_mfma_f32_4x4x1_16b_f32 v[210:213], v93, v104, v[210:213]
	v_mfma_f32_4x4x1_16b_f32 v[214:217], v93, v105, v[214:217]
	v_mfma_f32_4x4x1_16b_f32 v[228:231], v93, v106, v[228:231]
	v_mfma_f32_4x4x1_16b_f32 v[232:235], v93, v107, v[232:235]
	ds_read_b32 v93, v169 offset:3904
	s_waitcnt vmcnt(3) lgkmcnt(1)
; DI void attn_item(const P& p, int b, int kvh, int quad4, char* smem, const AttnPre& pre) {
;     ...
; #pragma unroll 1
;   for (int n0 = 0; n0 < 256; n0 += 64) {
;     uint2 vv[16];
; #pragma unroll
;     for (int u = 0; u < 16; ++u) vv[u] = *(const uint2*)(vb + (size_t)idx[n0 + 4 * u + quad] * 256);
; #pragma unroll
;     for (int u = 0; u < 16; ++u) {
;       const float4 p4 = *(const float4*)(L + (n0 + 4 * u + quad) * 4);
;       const f32x2_t c0 = __builtin_amdgcn_cvt_pk_f32_fp8((int)vv[u].x, false), c1 = __builtin_amdgcn_cvt_pk_f32_fp8((int)vv[u].x, true);
;       const f32x2_t c2 = __builtin_amdgcn_cvt_pk_f32_fp8((int)vv[u].y, false), c3 = __builtin_amdgcn_cvt_pk_f32_fp8((int)vv[u].y, true);
;       const float vf[8] = {c0.x, c0.y, c1.x, c1.y, c2.x, c2.y, c3.x, c3.y};
; #pragma unroll
;       for (int e = 0; e < 8; ++e) {
;         o[0][e] = fmaf(p4.x, vf[e], o[0][e]); o[1][e] = fmaf(p4.y, vf[e], o[1][e]);
;         o[2][e] = fmaf(p4.z, vf[e], o[2][e]); o[3][e] = fmaf(p4.w, vf[e], o[3][e]);
;       }
;     }
;   }
; #pragma unroll
;   for (int h = 0; h < 4; ++h)
; #pragma unroll
;     for (int e = 0; e < 8; ++e) { float v = o[h][e]; v += __shfl_xor(v, 16); v += __shfl_xor(v, 32); o[h][e] = v; }
	v_cvt_pk_f32_fp8_e32 v[100:101], v144
	v_cvt_pk_f32_fp8_sdwa v[102:103], v144 src0_sel:WORD_1
	v_cvt_pk_f32_fp8_e32 v[104:105], v145
	v_cvt_pk_f32_fp8_sdwa v[106:107], v145 src0_sel:WORD_1
	v_mfma_f32_4x4x1_16b_f32 v[194:197], v92, v100, v[194:197]
	v_mfma_f32_4x4x1_16b_f32 v[198:201], v92, v101, v[198:201]
	v_mfma_f32_4x4x1_16b_f32 v[202:205], v92, v102, v[202:205]
	v_mfma_f32_4x4x1_16b_f32 v[206:209], v92, v103, v[206:209]
	v_mfma_f32_4x4x1_16b_f32 v[210:213], v92, v104, v[210:213]
	v_mfma_f32_4x4x1_16b_f32 v[214:217], v92, v105, v[214:217]
	v_mfma_f32_4x4x1_16b_f32 v[228:231], v92, v106, v[228:231]
	v_mfma_f32_4x4x1_16b_f32 v[232:235], v92, v107, v[232:235]
	ds_read_b32 v92, v169 offset:3968
	s_waitcnt vmcnt(2) lgkmcnt(1)
	v_cvt_pk_f32_fp8_e32 v[100:101], v146
	v_cvt_pk_f32_fp8_sdwa v[102:103], v146 src0_sel:WORD_1
	v_cvt_pk_f32_fp8_e32 v[104:105], v147
	v_cvt_pk_f32_fp8_sdwa v[106:107], v147 src0_sel:WORD_1
	v_mfma_f32_4x4x1_16b_f32 v[194:197], v93, v100, v[194:197]
	v_mfma_f32_4x4x1_16b_f32 v[198:201], v93, v101, v[198:201]
	v_mfma_f32_4x4x1_16b_f32 v[202:205], v93, v102, v[202:205]
	v_mfma_f32_4x4x1_16b_f32 v[206:209], v93, v103, v[206:209]
	v_mfma_f32_4x4x1_16b_f32 v[210:213], v93, v104, v[210:213]
	v_mfma_f32_4x4x1_16b_f32 v[214:217], v93, v105, v[214:217]
	v_mfma_f32_4x4x1_16b_f32 v[228:231], v93, v106, v[228:231]
	v_mfma_f32_4x4x1_16b_f32 v[232:235], v93, v107, v[232:235]
	ds_read_b32 v93, v169 offset:4032
	s_waitcnt vmcnt(1) lgkmcnt(1)
	v_cvt_pk_f32_fp8_e32 v[100:101], v148
	v_cvt_pk_f32_fp8_sdwa v[102:103], v148 src0_sel:WORD_1
	v_cvt_pk_f32_fp8_e32 v[104:105], v149
	v_cvt_pk_f32_fp8_sdwa v[106:107], v149 src0_sel:WORD_1
	v_mfma_f32_4x4x1_16b_f32 v[194:197], v92, v100, v[194:197]
	v_mfma_f32_4x4x1_16b_f32 v[198:201], v92, v101, v[198:201]
	v_mfma_f32_4x4x1_16b_f32 v[202:205], v92, v102, v[202:205]
	v_mfma_f32_4x4x1_16b_f32 v[206:209], v92, v103, v[206:209]
	v_mfma_f32_4x4x1_16b_f32 v[210:213], v92, v104, v[210:213]
	v_mfma_f32_4x4x1_16b_f32 v[214:217], v92, v105, v[214:217]
	v_mfma_f32_4x4x1_16b_f32 v[228:231], v92, v106, v[228:231]
	v_mfma_f32_4x4x1_16b_f32 v[232:235], v92, v107, v[232:235]
	s_waitcnt vmcnt(0) lgkmcnt(0)
	v_cvt_pk_f32_fp8_e32 v[100:101], v150
	v_cvt_pk_f32_fp8_sdwa v[102:103], v150 src0_sel:WORD_1
	v_cvt_pk_f32_fp8_e32 v[104:105], v151
	v_cvt_pk_f32_fp8_sdwa v[106:107], v151 src0_sel:WORD_1
	v_mfma_f32_4x4x1_16b_f32 v[194:197], v93, v100, v[194:197]
	v_mfma_f32_4x4x1_16b_f32 v[198:201], v93, v101, v[198:201]
	v_mfma_f32_4x4x1_16b_f32 v[202:205], v93, v102, v[202:205]
	v_mfma_f32_4x4x1_16b_f32 v[206:209], v93, v103, v[206:209]
	v_mfma_f32_4x4x1_16b_f32 v[210:213], v93, v104, v[210:213]
	v_mfma_f32_4x4x1_16b_f32 v[214:217], v93, v105, v[214:217]
	v_mfma_f32_4x4x1_16b_f32 v[228:231], v93, v106, v[228:231]
	v_mfma_f32_4x4x1_16b_f32 v[232:235], v93, v107, v[232:235]
	s_nop 3
	v_mov_b32_e32 v48, v194
	v_mov_b32_e32 v44, v195
	v_mov_b32_e32 v38, v196
	v_mov_b32_e32 v30, v197
	v_mov_b32_e32 v49, v198
	v_mov_b32_e32 v45, v199
	v_mov_b32_e32 v39, v200
	v_mov_b32_e32 v31, v201
	v_mov_b32_e32 v46, v202
	v_mov_b32_e32 v42, v203
	v_mov_b32_e32 v34, v204
	v_mov_b32_e32 v26, v205
	v_mov_b32_e32 v47, v206
	v_mov_b32_e32 v43, v207
	v_mov_b32_e32 v35, v208
	v_mov_b32_e32 v27, v209
	v_mov_b32_e32 v40, v210
	v_mov_b32_e32 v32, v211
	v_mov_b32_e32 v22, v212
	v_mov_b32_e32 v18, v213
	v_mov_b32_e32 v41, v214
	v_mov_b32_e32 v33, v215
	v_mov_b32_e32 v23, v216
	v_mov_b32_e32 v19, v217
	v_mov_b32_e32 v36, v228
	v_mov_b32_e32 v28, v229
	v_mov_b32_e32 v20, v230
	v_mov_b32_e32 v16, v231
	v_mov_b32_e32 v37, v232
	v_mov_b32_e32 v29, v233
	v_mov_b32_e32 v21, v234
	v_mov_b32_e32 v17, v235
	ds_bpermute_b32 v24, v85, v48
	ds_bpermute_b32 v25, v85, v49
	ds_bpermute_b32 v50, v85, v46
	ds_bpermute_b32 v51, v85, v47
	ds_bpermute_b32 v52, v85, v40
	ds_bpermute_b32 v53, v85, v41
	ds_bpermute_b32 v54, v85, v36
	ds_bpermute_b32 v55, v85, v37
	ds_bpermute_b32 v56, v85, v44
	ds_bpermute_b32 v57, v85, v45
	ds_bpermute_b32 v58, v85, v42
	ds_bpermute_b32 v59, v85, v43
	ds_bpermute_b32 v60, v85, v32
	ds_bpermute_b32 v61, v85, v33
	ds_bpermute_b32 v62, v85, v28
	ds_bpermute_b32 v63, v85, v29
	ds_bpermute_b32 v64, v85, v38
	ds_bpermute_b32 v65, v85, v39
	ds_bpermute_b32 v66, v85, v34
	ds_bpermute_b32 v67, v85, v35
	ds_bpermute_b32 v68, v85, v22
	ds_bpermute_b32 v69, v85, v23
	ds_bpermute_b32 v70, v85, v20
	ds_bpermute_b32 v71, v85, v21
	ds_bpermute_b32 v72, v85, v30
	ds_bpermute_b32 v73, v85, v31
	ds_bpermute_b32 v74, v85, v26
	ds_bpermute_b32 v75, v85, v27
	ds_bpermute_b32 v76, v85, v18
	ds_bpermute_b32 v77, v85, v19
	ds_bpermute_b32 v78, v85, v16
	ds_bpermute_b32 v79, v85, v17
	s_waitcnt lgkmcnt(14)
	v_pk_add_f32 v[24:25], v[48:49], v[24:25]
	v_pk_add_f32 v[46:47], v[46:47], v[50:51]
	v_pk_add_f32 v[40:41], v[40:41], v[52:53]
	v_pk_add_f32 v[36:37], v[36:37], v[54:55]
	v_pk_add_f32 v[44:45], v[44:45], v[56:57]
	v_pk_add_f32 v[42:43], v[42:43], v[58:59]
	v_pk_add_f32 v[32:33], v[32:33], v[60:61]
	v_pk_add_f32 v[28:29], v[28:29], v[62:63]
	v_pk_add_f32 v[38:39], v[38:39], v[64:65]
	s_waitcnt lgkmcnt(12)
	v_pk_add_f32 v[34:35], v[34:35], v[66:67]
	s_waitcnt lgkmcnt(10)
	v_pk_add_f32 v[22:23], v[22:23], v[68:69]
	s_waitcnt lgkmcnt(8)
	v_pk_add_f32 v[20:21], v[20:21], v[70:71]
	s_waitcnt lgkmcnt(6)
	v_pk_add_f32 v[30:31], v[30:31], v[72:73]
	s_waitcnt lgkmcnt(4)
	v_pk_add_f32 v[26:27], v[26:27], v[74:75]
	s_waitcnt lgkmcnt(2)
	v_pk_add_f32 v[18:19], v[18:19], v[76:77]
	s_waitcnt lgkmcnt(0)
	v_pk_add_f32 v[16:17], v[16:17], v[78:79]
	ds_bpermute_b32 v48, v84, v24
	ds_bpermute_b32 v49, v84, v25
	ds_bpermute_b32 v50, v84, v46
	ds_bpermute_b32 v51, v84, v47
	ds_bpermute_b32 v52, v84, v40
	ds_bpermute_b32 v53, v84, v41
	ds_bpermute_b32 v54, v84, v36
	ds_bpermute_b32 v55, v84, v37
	ds_bpermute_b32 v56, v84, v44
	ds_bpermute_b32 v57, v84, v45
	ds_bpermute_b32 v58, v84, v42
	ds_bpermute_b32 v59, v84, v43
	ds_bpermute_b32 v60, v84, v32
	ds_bpermute_b32 v61, v84, v33
	ds_bpermute_b32 v62, v84, v28
	ds_bpermute_b32 v63, v84, v29
	ds_bpermute_b32 v64, v84, v38
	ds_bpermute_b32 v65, v84, v39
	ds_bpermute_b32 v66, v84, v34
	ds_bpermute_b32 v67, v84, v35
	ds_bpermute_b32 v68, v84, v22
	ds_bpermute_b32 v69, v84, v23
	ds_bpermute_b32 v70, v84, v20
	ds_bpermute_b32 v71, v84, v21
	ds_bpermute_b32 v72, v84, v30
	ds_bpermute_b32 v73, v84, v31
	ds_bpermute_b32 v74, v84, v26
	ds_bpermute_b32 v75, v84, v27
	ds_bpermute_b32 v76, v84, v18
	ds_bpermute_b32 v77, v84, v19
	ds_bpermute_b32 v78, v84, v16
	ds_bpermute_b32 v79, v84, v17
	s_and_saveexec_b64 s[6:7], s[4:5]
	s_cbranch_execz .LBB0_304
; DI uint4 pack8(const float* v) { uint4 r; r.x = pack2(v[0], v[1]); r.y = pack2(v[2], v[3]); r.z = pack2(v[4], v[5]); r.w = pack2(v[6], v[7]); return r; }
; DI void attn_item(const P& p, int b, int kvh, int quad4, char* smem, const AttnPre& pre) {
;     ...
;     for (int e = 0; e < 8; ++e) { float v = o[h][e]; v += __shfl_xor(v, 16); v += __shfl_xor(v, 32); o[h][e] = v; }
;   if (quad == 0) {
; #pragma unroll
;     for (int h = 0; h < 4; ++h) *(uint4*)(p.q + tok * 1024 + (kvh * 4 + h) * 128 + r * 8) = pack8(o[h]);
;   }
	v_readlane_b32 s10, v250, 17
	s_waitcnt lgkmcnt(0)
	v_pk_add_f32 v[78:79], v[16:17], v[78:79]
	v_pk_add_f32 v[16:17], v[24:25], v[48:49]
	v_lshlrev_b64 v[24:25], 11, v[90:91]
	s_lshl_b32 s4, s9, 9
	v_readlane_b32 s11, v250, 18
	s_ashr_i32 s5, s4, 31
	v_pk_add_f32 v[76:77], v[18:19], v[76:77]
	v_lshl_add_u64 v[24:25], s[10:11], 0, v[24:25]
	v_pk_add_f32 v[36:37], v[36:37], v[54:55]
	v_pk_add_f32 v[18:19], v[40:41], v[52:53]
	v_pk_add_f32 v[40:41], v[46:47], v[50:51]
	v_lshl_add_u64 v[24:25], s[4:5], 1, v[24:25]
	v_lshlrev_b32_e32 v192, 1, v192
	v_pk_add_f32 v[28:29], v[28:29], v[62:63]
	v_pk_add_f32 v[32:33], v[32:33], v[60:61]
	v_pk_add_f32 v[42:43], v[42:43], v[58:59]
	v_pk_add_f32 v[44:45], v[44:45], v[56:57]
	v_cvt_pk_bf16_f32 v16, v16, v17
	v_cvt_pk_bf16_f32 v17, v40, v41
	v_cvt_pk_bf16_f32 v18, v18, v19
	v_cvt_pk_bf16_f32 v19, v36, v37
	v_lshl_add_u64 v[24:25], v[24:25], 0, v[192:193]
	v_pk_add_f32 v[20:21], v[20:21], v[70:71]
	v_pk_add_f32 v[22:23], v[22:23], v[68:69]
	v_pk_add_f32 v[34:35], v[34:35], v[66:67]
	v_pk_add_f32 v[38:39], v[38:39], v[64:65]
	global_store_dwordx4 v[24:25], v[16:19], off
	v_pk_add_f32 v[26:27], v[26:27], v[74:75]
	v_pk_add_f32 v[30:31], v[30:31], v[72:73]
	v_cvt_pk_bf16_f32 v16, v44, v45
	v_cvt_pk_bf16_f32 v17, v42, v43
	v_cvt_pk_bf16_f32 v18, v32, v33
	v_cvt_pk_bf16_f32 v19, v28, v29
	global_store_dwordx4 v[24:25], v[16:19], off offset:256
	s_nop 1
	v_cvt_pk_bf16_f32 v16, v38, v39
	v_cvt_pk_bf16_f32 v17, v34, v35
	v_cvt_pk_bf16_f32 v18, v22, v23
	v_cvt_pk_bf16_f32 v19, v20, v21
	global_store_dwordx4 v[24:25], v[16:19], off offset:512
	s_nop 1
	v_cvt_pk_bf16_f32 v16, v30, v31
	v_cvt_pk_bf16_f32 v17, v26, v27
	v_cvt_pk_bf16_f32 v18, v76, v77
	v_cvt_pk_bf16_f32 v19, v78, v79
	global_store_dwordx4 v[24:25], v[16:19], off offset:768
	s_branch .LBB0_304
